# attention loop: mid-step barrier moved from MFMA slot 12 to slot 14 (on top of the layer-0 modnorm replacement)
# baseline (speedup 1.0000x reference)
.Lat_k2_5:
	s_add_u32 s12, s12, 0x30000
	s_addc_u32 s13, s13, 0
	s_add_i32 m0, s22, 0x13000
	s_nop 0
	global_load_lds_dwordx4 v145, s[14:15]
	s_add_u32 s14, s14, 0x20000
	s_addc_u32 s15, s15, 0
	v_exp_f32_e32 v48, v48
	v_exp_f32_e32 v49, v49
	v_exp_f32_e32 v50, v50
	v_exp_f32_e32 v51, v51
	v_mov_b32_e32 v176, v48
	v_mov_b32_e32 v177, v49
	v_cvt_pk_bf16_f32 v48, v48, v49
	v_add_f32_e32 v176, v50, v176
	s_waitcnt lgkmcnt(8)
	v_mfma_f32_32x32x16_bf16 v[80:95], v[196:199], v[110:113], v[224:239]
	ds_read_b128 v[196:199], v194 offset:26624
	ds_read_b64_tr_b16 v[240:241], v139 offset:1024
	ds_read_b64_tr_b16 v[242:243], v139 offset:1536
	v_add_f32_e32 v177, v51, v177
	v_cvt_pk_bf16_f32 v49, v50, v51
	v_exp_f32_e32 v52, v52
	v_exp_f32_e32 v53, v53
	v_mfma_f32_32x32x16_bf16 v[64:79], v[200:203], v[110:113], v[224:239]
	ds_read_b128 v[200:203], v194 offset:27136
	ds_read_b64_tr_b16 v[122:123], v139 offset:5120
	ds_read_b64_tr_b16 v[124:125], v139 offset:5632
	v_exp_f32_e32 v54, v54
	v_exp_f32_e32 v55, v55
	v_add_f32_e32 v176, v52, v176
	v_add_f32_e32 v177, v53, v177
	s_waitcnt lgkmcnt(12)
	v_mfma_f32_32x32x16_bf16 v[80:95], v[204:207], v[106:109], v[80:95]
	ds_read_b128 v[204:207], v194 offset:28672
	v_cvt_pk_bf16_f32 v50, v52, v53
	v_add_f32_e32 v176, v54, v176
	v_add_f32_e32 v177, v55, v177
	v_cvt_pk_bf16_f32 v51, v54, v55
	v_mfma_f32_32x32x16_bf16 v[64:79], v[208:211], v[106:109], v[64:79]
	ds_read_b128 v[208:211], v194 offset:29184
	v_exp_f32_e32 v56, v56
	v_exp_f32_e32 v57, v57
	v_exp_f32_e32 v58, v58
	v_exp_f32_e32 v59, v59
	s_waitcnt lgkmcnt(8)
	v_mfma_f32_32x32x16_bf16 v[80:95], v[212:215], v[114:117], v[80:95]
	ds_read_b128 v[212:215], v194 offset:30720
	v_add_f32_e32 v176, v56, v176
	v_add_f32_e32 v177, v57, v177
	v_cvt_pk_bf16_f32 v52, v56, v57
	v_add_f32_e32 v176, v58, v176
	v_mfma_f32_32x32x16_bf16 v[0:15], v[48:51], v[220:223], v[0:15]
	ds_read_b64_tr_b16 v[220:221], v139 offset:2048
	ds_read_b64_tr_b16 v[222:223], v139 offset:2560
	v_add_f32_e32 v177, v59, v177
	v_cvt_pk_bf16_f32 v53, v58, v59
	v_exp_f32_e32 v60, v60
	v_exp_f32_e32 v61, v61
	v_mfma_f32_32x32x16_bf16 v[16:31], v[48:51], v[244:247], v[16:31]
	ds_read_b64_tr_b16 v[244:245], v139 offset:6144
	ds_read_b64_tr_b16 v[246:247], v139 offset:6656
	v_exp_f32_e32 v62, v62
	v_exp_f32_e32 v63, v63
	v_add_f32_e32 v176, v60, v176
	v_add_f32_e32 v177, v61, v177
	v_mfma_f32_32x32x16_bf16 v[64:79], v[216:219], v[114:117], v[64:79]
	ds_read_b128 v[216:219], v194 offset:31232
	v_cvt_pk_bf16_f32 v54, v60, v61
	v_add_f32_e32 v176, v62, v176
	v_add_f32_e32 v177, v63, v177
	v_cvt_pk_bf16_f32 v55, v62, v63
	s_waitcnt lgkmcnt(10)
	v_mfma_f32_32x32x16_bf16 v[80:95], v[196:199], v[118:121], v[80:95]
	v_exp_f32_e32 v32, v32
	v_exp_f32_e32 v33, v33
	v_exp_f32_e32 v34, v34
	v_exp_f32_e32 v35, v35
	v_mfma_f32_32x32x16_bf16 v[64:79], v[200:203], v[118:121], v[64:79]
	v_add_f32_e32 v176, v32, v176
	v_add_f32_e32 v177, v33, v177
	v_cvt_pk_bf16_f32 v32, v32, v33
	v_add_f32_e32 v176, v34, v176
	s_waitcnt lgkmcnt(8)
	v_mfma_f32_32x32x16_bf16 v[0:15], v[52:55], v[240:243], v[0:15]
	ds_read_b64_tr_b16 v[240:241], v139 offset:3072
	ds_read_b64_tr_b16 v[242:243], v139 offset:3584
	v_add_f32_e32 v177, v35, v177
	v_cvt_pk_bf16_f32 v33, v34, v35
	v_exp_f32_e32 v36, v36
	v_exp_f32_e32 v37, v37
	v_mfma_f32_32x32x16_bf16 v[16:31], v[52:55], v[122:125], v[16:31]
	ds_read_b64_tr_b16 v[122:123], v139 offset:7168
	ds_read_b64_tr_b16 v[124:125], v139 offset:7680
	v_exp_f32_e32 v38, v38
	v_exp_f32_e32 v39, v39
	v_add_f32_e32 v176, v36, v176
	v_add_f32_e32 v177, v37, v177
	s_waitcnt lgkmcnt(10)
	v_mfma_f32_32x32x16_bf16 v[80:95], v[204:207], v[102:105], v[80:95]
	v_cvt_pk_bf16_f32 v34, v36, v37
	v_add_f32_e32 v176, v38, v176
	v_add_f32_e32 v177, v39, v177
	v_cvt_pk_bf16_f32 v35, v38, v39
	v_mfma_f32_32x32x16_bf16 v[64:79], v[208:211], v[102:105], v[64:79]
	v_exp_f32_e32 v40, v40
	v_exp_f32_e32 v41, v41
	v_exp_f32_e32 v42, v42
	v_exp_f32_e32 v43, v43
	s_waitcnt vmcnt(2)
	s_barrier
	s_waitcnt lgkmcnt(5)
	v_mfma_f32_32x32x16_bf16 v[0:15], v[32:35], v[220:223], v[0:15]
	ds_read_b128 v[196:199], v126 offset:0
	ds_read_b128 v[200:203], v126 offset:512
	ds_read_b128 v[204:207], v126 offset:2048
	ds_read_b128 v[208:211], v126 offset:2560
	ds_read_b64_tr_b16 v[220:221], v139 offset:20480
	ds_read_b64_tr_b16 v[222:223], v139 offset:20992
	v_add_f32_e32 v176, v40, v176
	v_add_f32_e32 v177, v41, v177
	v_cvt_pk_bf16_f32 v36, v40, v41
	v_add_f32_e32 v176, v42, v176
	v_mfma_f32_32x32x16_bf16 v[16:31], v[32:35], v[244:247], v[16:31]
	ds_read_b64_tr_b16 v[244:245], v139 offset:24576
	ds_read_b64_tr_b16 v[246:247], v139 offset:25088
	v_add_f32_e32 v177, v43, v177
	v_cvt_pk_bf16_f32 v37, v42, v43
	v_exp_f32_e32 v44, v44
	v_exp_f32_e32 v45, v45
	s_waitcnt lgkmcnt(12)
	v_mfma_f32_32x32x16_bf16 v[80:95], v[212:215], v[98:101], v[80:95]
	ds_read_b128 v[212:215], v126 offset:4096
	v_exp_f32_e32 v46, v46
	v_exp_f32_e32 v47, v47
	v_add_f32_e32 v176, v44, v176
	v_add_f32_e32 v177, v45, v177
	v_mfma_f32_32x32x16_bf16 v[64:79], v[216:219], v[98:101], v[64:79]
	ds_read_b128 v[216:219], v126 offset:4608
	v_cvt_pk_bf16_f32 v38, v44, v45
	v_add_f32_e32 v176, v46, v176
	v_add_f32_e32 v177, v47, v177
	v_cvt_pk_bf16_f32 v39, v46, v47
	s_waitcnt lgkmcnt(10)
	v_mfma_f32_32x32x16_bf16 v[0:15], v[36:39], v[240:243], v[0:15]
	v_add_f32_e32 v175, v176, v177
	v_mov_b32_e32 v178, v175
	v_add_f32_e32 v147, v147, v175
	s_nop 0
	v_mfma_f32_32x32x16_bf16 v[16:31], v[36:39], v[122:125], v[16:31]
	v_permlane32_swap_b32_e32 v175, v178
	v_add_f32_e32 v175, v175, v178
	v_cmp_lt_f32_e32 vcc, 0x43800000, v175
	s_cbranch_vccz .Lat_nr_6
	v_log_f32_e32 v175, v175
	s_nop 0
	v_max_f32_e32 v175, 0, v175
	v_exp_f32_e64 v178, -v175
	s_and_saveexec_b64 s[4:5], s[2:3]
	ds_write_b32 v143, v178 offset:40960
	s_or_b64 exec, exec, s[4:5]
	s_waitcnt lgkmcnt(0)
	v_add_u32_e32 v179, s33, v191
	v_sub_f32_e32 v224, v224, v175
	v_mul_f32_e32 v147, v147, v178
	ds_read_b128 v[48:51], v179 offset:40960
	ds_read_b128 v[52:55], v179 offset:40992
	ds_read_b128 v[56:59], v179 offset:41024
	ds_read_b128 v[60:63], v179 offset:41056
	s_waitcnt lgkmcnt(0)
	s_nop 15
	v_pk_mul_f32 v[0:1], v[0:1], v[48:49]
	v_pk_mul_f32 v[2:3], v[2:3], v[50:51]
	v_pk_mul_f32 v[4:5], v[4:5], v[52:53]
	v_pk_mul_f32 v[6:7], v[6:7], v[54:55]
	v_pk_mul_f32 v[8:9], v[8:9], v[56:57]
	v_pk_mul_f32 v[10:11], v[10:11], v[58:59]
	v_pk_mul_f32 v[12:13], v[12:13], v[60:61]
	v_pk_mul_f32 v[14:15], v[14:15], v[62:63]
	v_pk_mul_f32 v[16:17], v[16:17], v[48:49]
	v_pk_mul_f32 v[18:19], v[18:19], v[50:51]
	v_pk_mul_f32 v[20:21], v[20:21], v[52:53]
	v_pk_mul_f32 v[22:23], v[22:23], v[54:55]
	v_pk_mul_f32 v[24:25], v[24:25], v[56:57]
	v_pk_mul_f32 v[26:27], v[26:27], v[58:59]
	v_pk_mul_f32 v[28:29], v[28:29], v[60:61]
	v_pk_mul_f32 v[30:31], v[30:31], v[62:63]
	v_mov_b32_e32 v225, v224
	v_mov_b32_e32 v226, v224
	v_mov_b32_e32 v227, v224
	v_mov_b32_e32 v228, v224
	v_mov_b32_e32 v229, v224
	v_mov_b32_e32 v230, v224
	v_mov_b32_e32 v231, v224
	v_mov_b32_e32 v232, v224
	v_mov_b32_e32 v233, v224
	v_mov_b32_e32 v234, v224
	v_mov_b32_e32 v235, v224
	v_mov_b32_e32 v236, v224
	v_mov_b32_e32 v237, v224
	v_mov_b32_e32 v238, v224
	v_mov_b32_e32 v239, v224
	v_sub_f32_e32 v80, v80, v175
	v_sub_f32_e32 v81, v81, v175
	v_sub_f32_e32 v82, v82, v175
	v_sub_f32_e32 v83, v83, v175
	v_sub_f32_e32 v84, v84, v175
	v_sub_f32_e32 v85, v85, v175
	v_sub_f32_e32 v86, v86, v175
	v_sub_f32_e32 v87, v87, v175
	v_sub_f32_e32 v88, v88, v175
	v_sub_f32_e32 v89, v89, v175
	v_sub_f32_e32 v90, v90, v175
	v_sub_f32_e32 v91, v91, v175
	v_sub_f32_e32 v92, v92, v175
	v_sub_f32_e32 v93, v93, v175
	v_sub_f32_e32 v94, v94, v175
	v_sub_f32_e32 v95, v95, v175
	v_sub_f32_e32 v64, v64, v175
	v_sub_f32_e32 v65, v65, v175
	v_sub_f32_e32 v66, v66, v175
	v_sub_f32_e32 v67, v67, v175
	v_sub_f32_e32 v68, v68, v175
	v_sub_f32_e32 v69, v69, v175
	v_sub_f32_e32 v70, v70, v175
	v_sub_f32_e32 v71, v71, v175
	v_sub_f32_e32 v72, v72, v175
	v_sub_f32_e32 v73, v73, v175
	v_sub_f32_e32 v74, v74, v175
	v_sub_f32_e32 v75, v75, v175
	v_sub_f32_e32 v76, v76, v175
	v_sub_f32_e32 v77, v77, v175
	v_sub_f32_e32 v78, v78, v175
	v_sub_f32_e32 v79, v79, v175

.Lat_k2_7:
	s_add_u32 s12, s12, 0x30000
	s_addc_u32 s13, s13, 0
	s_add_i32 m0, s22, 0x18000
	s_nop 0
	global_load_lds_dwordx4 v145, s[14:15]
	s_add_u32 s14, s14, 0x20000
	s_addc_u32 s15, s15, 0
	v_exp_f32_e32 v80, v80
	v_exp_f32_e32 v81, v81
	v_exp_f32_e32 v82, v82
	v_exp_f32_e32 v83, v83
	v_mov_b32_e32 v176, v80
	v_mov_b32_e32 v177, v81
	v_cvt_pk_bf16_f32 v80, v80, v81
	v_add_f32_e32 v176, v82, v176
	s_waitcnt lgkmcnt(8)
	v_mfma_f32_32x32x16_bf16 v[48:63], v[196:199], v[110:113], v[224:239]
	ds_read_b128 v[196:199], v126 offset:6144
	ds_read_b64_tr_b16 v[240:241], v139 offset:21504
	ds_read_b64_tr_b16 v[242:243], v139 offset:22016
	v_add_f32_e32 v177, v83, v177
	v_cvt_pk_bf16_f32 v81, v82, v83
	v_exp_f32_e32 v84, v84
	v_exp_f32_e32 v85, v85
	v_mfma_f32_32x32x16_bf16 v[32:47], v[200:203], v[110:113], v[224:239]
	ds_read_b128 v[200:203], v126 offset:6656
	ds_read_b64_tr_b16 v[122:123], v139 offset:25600
	ds_read_b64_tr_b16 v[124:125], v139 offset:26112
	v_exp_f32_e32 v86, v86
	v_exp_f32_e32 v87, v87
	v_add_f32_e32 v176, v84, v176
	v_add_f32_e32 v177, v85, v177
	s_waitcnt lgkmcnt(12)
	v_mfma_f32_32x32x16_bf16 v[48:63], v[204:207], v[106:109], v[48:63]
	ds_read_b128 v[204:207], v126 offset:8192
	v_cvt_pk_bf16_f32 v82, v84, v85
	v_add_f32_e32 v176, v86, v176
	v_add_f32_e32 v177, v87, v177
	v_cvt_pk_bf16_f32 v83, v86, v87
	v_mfma_f32_32x32x16_bf16 v[32:47], v[208:211], v[106:109], v[32:47]
	ds_read_b128 v[208:211], v126 offset:8704
	v_exp_f32_e32 v88, v88
	v_exp_f32_e32 v89, v89
	v_exp_f32_e32 v90, v90
	v_exp_f32_e32 v91, v91
	s_waitcnt lgkmcnt(8)
	v_mfma_f32_32x32x16_bf16 v[48:63], v[212:215], v[114:117], v[48:63]
	ds_read_b128 v[212:215], v126 offset:10240
	v_add_f32_e32 v176, v88, v176
	v_add_f32_e32 v177, v89, v177
	v_cvt_pk_bf16_f32 v84, v88, v89
	v_add_f32_e32 v176, v90, v176
	v_mfma_f32_32x32x16_bf16 v[0:15], v[80:83], v[220:223], v[0:15]
	ds_read_b64_tr_b16 v[220:221], v139 offset:22528
	ds_read_b64_tr_b16 v[222:223], v139 offset:23040
	v_add_f32_e32 v177, v91, v177
	v_cvt_pk_bf16_f32 v85, v90, v91
	v_exp_f32_e32 v92, v92
	v_exp_f32_e32 v93, v93
	v_mfma_f32_32x32x16_bf16 v[16:31], v[80:83], v[244:247], v[16:31]
	ds_read_b64_tr_b16 v[244:245], v139 offset:26624
	ds_read_b64_tr_b16 v[246:247], v139 offset:27136
	v_exp_f32_e32 v94, v94
	v_exp_f32_e32 v95, v95
	v_add_f32_e32 v176, v92, v176
	v_add_f32_e32 v177, v93, v177
	v_mfma_f32_32x32x16_bf16 v[32:47], v[216:219], v[114:117], v[32:47]
	ds_read_b128 v[216:219], v126 offset:10752
	v_cvt_pk_bf16_f32 v86, v92, v93
	v_add_f32_e32 v176, v94, v176
	v_add_f32_e32 v177, v95, v177
	v_cvt_pk_bf16_f32 v87, v94, v95
	s_waitcnt lgkmcnt(10)
	v_mfma_f32_32x32x16_bf16 v[48:63], v[196:199], v[118:121], v[48:63]
	v_exp_f32_e32 v64, v64
	v_exp_f32_e32 v65, v65
	v_exp_f32_e32 v66, v66
	v_exp_f32_e32 v67, v67
	v_mfma_f32_32x32x16_bf16 v[32:47], v[200:203], v[118:121], v[32:47]
	v_add_f32_e32 v176, v64, v176
	v_add_f32_e32 v177, v65, v177
	v_cvt_pk_bf16_f32 v64, v64, v65
	v_add_f32_e32 v176, v66, v176
	s_waitcnt lgkmcnt(8)
	v_mfma_f32_32x32x16_bf16 v[0:15], v[84:87], v[240:243], v[0:15]
	ds_read_b64_tr_b16 v[240:241], v139 offset:23552
	ds_read_b64_tr_b16 v[242:243], v139 offset:24064
	v_add_f32_e32 v177, v67, v177
	v_cvt_pk_bf16_f32 v65, v66, v67
	v_exp_f32_e32 v68, v68
	v_exp_f32_e32 v69, v69
	v_mfma_f32_32x32x16_bf16 v[16:31], v[84:87], v[122:125], v[16:31]
	ds_read_b64_tr_b16 v[122:123], v139 offset:27648
	ds_read_b64_tr_b16 v[124:125], v139 offset:28160
	v_exp_f32_e32 v70, v70
	v_exp_f32_e32 v71, v71
	v_add_f32_e32 v176, v68, v176
	v_add_f32_e32 v177, v69, v177
	s_waitcnt lgkmcnt(10)
	v_mfma_f32_32x32x16_bf16 v[48:63], v[204:207], v[102:105], v[48:63]
	v_cvt_pk_bf16_f32 v66, v68, v69
	v_add_f32_e32 v176, v70, v176
	v_add_f32_e32 v177, v71, v177
	v_cvt_pk_bf16_f32 v67, v70, v71
	v_mfma_f32_32x32x16_bf16 v[32:47], v[208:211], v[102:105], v[32:47]
	v_exp_f32_e32 v72, v72
	v_exp_f32_e32 v73, v73
	v_exp_f32_e32 v74, v74
	v_exp_f32_e32 v75, v75
	s_waitcnt vmcnt(2)
	s_barrier
	s_waitcnt lgkmcnt(5)
	v_mfma_f32_32x32x16_bf16 v[0:15], v[64:67], v[220:223], v[0:15]
	ds_read_b128 v[196:199], v126 offset:20480
	ds_read_b128 v[200:203], v126 offset:20992
	ds_read_b128 v[204:207], v126 offset:22528
	ds_read_b128 v[208:211], v126 offset:23040
	ds_read_b64_tr_b16 v[220:221], v127 offset:0
	ds_read_b64_tr_b16 v[222:223], v127 offset:512
	v_add_f32_e32 v176, v72, v176
	v_add_f32_e32 v177, v73, v177
	v_cvt_pk_bf16_f32 v68, v72, v73
	v_add_f32_e32 v176, v74, v176
	v_mfma_f32_32x32x16_bf16 v[16:31], v[64:67], v[244:247], v[16:31]
	ds_read_b64_tr_b16 v[244:245], v127 offset:4096
	ds_read_b64_tr_b16 v[246:247], v127 offset:4608
	v_add_f32_e32 v177, v75, v177
	v_cvt_pk_bf16_f32 v69, v74, v75
	v_exp_f32_e32 v76, v76
	v_exp_f32_e32 v77, v77
	s_waitcnt lgkmcnt(12)
	v_mfma_f32_32x32x16_bf16 v[48:63], v[212:215], v[98:101], v[48:63]
	ds_read_b128 v[212:215], v126 offset:24576
	v_exp_f32_e32 v78, v78
	v_exp_f32_e32 v79, v79
	v_add_f32_e32 v176, v76, v176
	v_add_f32_e32 v177, v77, v177
	v_mfma_f32_32x32x16_bf16 v[32:47], v[216:219], v[98:101], v[32:47]
	ds_read_b128 v[216:219], v126 offset:25088
	v_cvt_pk_bf16_f32 v70, v76, v77
	v_add_f32_e32 v176, v78, v176
	v_add_f32_e32 v177, v79, v177
	v_cvt_pk_bf16_f32 v71, v78, v79
	s_waitcnt lgkmcnt(10)
	v_mfma_f32_32x32x16_bf16 v[0:15], v[68:71], v[240:243], v[0:15]
	v_add_f32_e32 v175, v176, v177
	v_mov_b32_e32 v178, v175
	v_add_f32_e32 v147, v147, v175
	s_nop 0
	v_mfma_f32_32x32x16_bf16 v[16:31], v[68:71], v[122:125], v[16:31]
	v_permlane32_swap_b32_e32 v175, v178
	v_add_f32_e32 v175, v175, v178
	v_cmp_lt_f32_e32 vcc, 0x43800000, v175
	s_cbranch_vccz .Lat_nr_8
	v_log_f32_e32 v175, v175
	s_nop 0
	v_max_f32_e32 v175, 0, v175
	v_exp_f32_e64 v178, -v175
	s_and_saveexec_b64 s[4:5], s[2:3]
	ds_write_b32 v143, v178 offset:40960
	s_or_b64 exec, exec, s[4:5]
	s_waitcnt lgkmcnt(0)
	v_add_u32_e32 v179, s33, v191
	v_sub_f32_e32 v224, v224, v175
	v_mul_f32_e32 v147, v147, v178
	ds_read_b128 v[80:83], v179 offset:40960
	ds_read_b128 v[84:87], v179 offset:40992
	ds_read_b128 v[88:91], v179 offset:41024
	ds_read_b128 v[92:95], v179 offset:41056
	s_waitcnt lgkmcnt(0)
	s_nop 15
	v_pk_mul_f32 v[0:1], v[0:1], v[80:81]
	v_pk_mul_f32 v[2:3], v[2:3], v[82:83]
	v_pk_mul_f32 v[4:5], v[4:5], v[84:85]
	v_pk_mul_f32 v[6:7], v[6:7], v[86:87]
	v_pk_mul_f32 v[8:9], v[8:9], v[88:89]
	v_pk_mul_f32 v[10:11], v[10:11], v[90:91]
	v_pk_mul_f32 v[12:13], v[12:13], v[92:93]
	v_pk_mul_f32 v[14:15], v[14:15], v[94:95]
	v_pk_mul_f32 v[16:17], v[16:17], v[80:81]
	v_pk_mul_f32 v[18:19], v[18:19], v[82:83]
	v_pk_mul_f32 v[20:21], v[20:21], v[84:85]
	v_pk_mul_f32 v[22:23], v[22:23], v[86:87]
	v_pk_mul_f32 v[24:25], v[24:25], v[88:89]
	v_pk_mul_f32 v[26:27], v[26:27], v[90:91]
	v_pk_mul_f32 v[28:29], v[28:29], v[92:93]
	v_pk_mul_f32 v[30:31], v[30:31], v[94:95]
	v_mov_b32_e32 v225, v224
	v_mov_b32_e32 v226, v224
	v_mov_b32_e32 v227, v224
	v_mov_b32_e32 v228, v224
	v_mov_b32_e32 v229, v224
	v_mov_b32_e32 v230, v224
	v_mov_b32_e32 v231, v224
	v_mov_b32_e32 v232, v224
	v_mov_b32_e32 v233, v224
	v_mov_b32_e32 v234, v224
	v_mov_b32_e32 v235, v224
	v_mov_b32_e32 v236, v224
	v_mov_b32_e32 v237, v224
	v_mov_b32_e32 v238, v224
	v_mov_b32_e32 v239, v224
	v_sub_f32_e32 v48, v48, v175
	v_sub_f32_e32 v49, v49, v175
	v_sub_f32_e32 v50, v50, v175
	v_sub_f32_e32 v51, v51, v175
	v_sub_f32_e32 v52, v52, v175
	v_sub_f32_e32 v53, v53, v175
	v_sub_f32_e32 v54, v54, v175
	v_sub_f32_e32 v55, v55, v175
	v_sub_f32_e32 v56, v56, v175
	v_sub_f32_e32 v57, v57, v175
	v_sub_f32_e32 v58, v58, v175
	v_sub_f32_e32 v59, v59, v175
	v_sub_f32_e32 v60, v60, v175
	v_sub_f32_e32 v61, v61, v175
	v_sub_f32_e32 v62, v62, v175
	v_sub_f32_e32 v63, v63, v175
	v_sub_f32_e32 v32, v32, v175
	v_sub_f32_e32 v33, v33, v175
	v_sub_f32_e32 v34, v34, v175
	v_sub_f32_e32 v35, v35, v175
	v_sub_f32_e32 v36, v36, v175
	v_sub_f32_e32 v37, v37, v175
	v_sub_f32_e32 v38, v38, v175
	v_sub_f32_e32 v39, v39, v175
	v_sub_f32_e32 v40, v40, v175
	v_sub_f32_e32 v41, v41, v175
	v_sub_f32_e32 v42, v42, v175
	v_sub_f32_e32 v43, v43, v175
	v_sub_f32_e32 v44, v44, v175
	v_sub_f32_e32 v45, v45, v175
	v_sub_f32_e32 v46, v46, v175
	v_sub_f32_e32 v47, v47, v175

.Lat_k2_9:
	s_add_u32 s12, s12, 0x30000
	s_addc_u32 s13, s13, 0
	s_add_i32 m0, s22, 0x3000
	s_nop 0
	global_load_lds_dwordx4 v145, s[14:15]
	s_add_u32 s14, s14, 0x20000
	s_addc_u32 s15, s15, 0
	v_exp_f32_e32 v48, v48
	v_exp_f32_e32 v49, v49
	v_exp_f32_e32 v50, v50
	v_exp_f32_e32 v51, v51
	v_mov_b32_e32 v176, v48
	v_mov_b32_e32 v177, v49
	v_cvt_pk_bf16_f32 v48, v48, v49
	v_add_f32_e32 v176, v50, v176
	s_waitcnt lgkmcnt(8)
	v_mfma_f32_32x32x16_bf16 v[80:95], v[196:199], v[110:113], v[224:239]
	ds_read_b128 v[196:199], v126 offset:26624
	ds_read_b64_tr_b16 v[240:241], v127 offset:1024
	ds_read_b64_tr_b16 v[242:243], v127 offset:1536
	v_add_f32_e32 v177, v51, v177
	v_cvt_pk_bf16_f32 v49, v50, v51
	v_exp_f32_e32 v52, v52
	v_exp_f32_e32 v53, v53
	v_mfma_f32_32x32x16_bf16 v[64:79], v[200:203], v[110:113], v[224:239]
	ds_read_b128 v[200:203], v126 offset:27136
	ds_read_b64_tr_b16 v[122:123], v127 offset:5120
	ds_read_b64_tr_b16 v[124:125], v127 offset:5632
	v_exp_f32_e32 v54, v54
	v_exp_f32_e32 v55, v55
	v_add_f32_e32 v176, v52, v176
	v_add_f32_e32 v177, v53, v177
	s_waitcnt lgkmcnt(12)
	v_mfma_f32_32x32x16_bf16 v[80:95], v[204:207], v[106:109], v[80:95]
	ds_read_b128 v[204:207], v126 offset:28672
	v_cvt_pk_bf16_f32 v50, v52, v53
	v_add_f32_e32 v176, v54, v176
	v_add_f32_e32 v177, v55, v177
	v_cvt_pk_bf16_f32 v51, v54, v55
	v_mfma_f32_32x32x16_bf16 v[64:79], v[208:211], v[106:109], v[64:79]
	ds_read_b128 v[208:211], v126 offset:29184
	v_exp_f32_e32 v56, v56
	v_exp_f32_e32 v57, v57
	v_exp_f32_e32 v58, v58
	v_exp_f32_e32 v59, v59
	s_waitcnt lgkmcnt(8)
	v_mfma_f32_32x32x16_bf16 v[80:95], v[212:215], v[114:117], v[80:95]
	ds_read_b128 v[212:215], v126 offset:30720
	v_add_f32_e32 v176, v56, v176
	v_add_f32_e32 v177, v57, v177
	v_cvt_pk_bf16_f32 v52, v56, v57
	v_add_f32_e32 v176, v58, v176
	v_mfma_f32_32x32x16_bf16 v[0:15], v[48:51], v[220:223], v[0:15]
	ds_read_b64_tr_b16 v[220:221], v127 offset:2048
	ds_read_b64_tr_b16 v[222:223], v127 offset:2560
	v_add_f32_e32 v177, v59, v177
	v_cvt_pk_bf16_f32 v53, v58, v59
	v_exp_f32_e32 v60, v60
	v_exp_f32_e32 v61, v61
	v_mfma_f32_32x32x16_bf16 v[16:31], v[48:51], v[244:247], v[16:31]
	ds_read_b64_tr_b16 v[244:245], v127 offset:6144
	ds_read_b64_tr_b16 v[246:247], v127 offset:6656
	v_exp_f32_e32 v62, v62
	v_exp_f32_e32 v63, v63
	v_add_f32_e32 v176, v60, v176
	v_add_f32_e32 v177, v61, v177
	v_mfma_f32_32x32x16_bf16 v[64:79], v[216:219], v[114:117], v[64:79]
	ds_read_b128 v[216:219], v126 offset:31232
	v_cvt_pk_bf16_f32 v54, v60, v61
	v_add_f32_e32 v176, v62, v176
	v_add_f32_e32 v177, v63, v177
	v_cvt_pk_bf16_f32 v55, v62, v63
	s_waitcnt lgkmcnt(10)
	v_mfma_f32_32x32x16_bf16 v[80:95], v[196:199], v[118:121], v[80:95]
	v_exp_f32_e32 v32, v32
	v_exp_f32_e32 v33, v33
	v_exp_f32_e32 v34, v34
	v_exp_f32_e32 v35, v35
	v_mfma_f32_32x32x16_bf16 v[64:79], v[200:203], v[118:121], v[64:79]
	v_add_f32_e32 v176, v32, v176
	v_add_f32_e32 v177, v33, v177
	v_cvt_pk_bf16_f32 v32, v32, v33
	v_add_f32_e32 v176, v34, v176
	s_waitcnt lgkmcnt(8)
	v_mfma_f32_32x32x16_bf16 v[0:15], v[52:55], v[240:243], v[0:15]
	ds_read_b64_tr_b16 v[240:241], v127 offset:3072
	ds_read_b64_tr_b16 v[242:243], v127 offset:3584
	v_add_f32_e32 v177, v35, v177
	v_cvt_pk_bf16_f32 v33, v34, v35
	v_exp_f32_e32 v36, v36
	v_exp_f32_e32 v37, v37
	v_mfma_f32_32x32x16_bf16 v[16:31], v[52:55], v[122:125], v[16:31]
	ds_read_b64_tr_b16 v[122:123], v127 offset:7168
	ds_read_b64_tr_b16 v[124:125], v127 offset:7680
	v_exp_f32_e32 v38, v38
	v_exp_f32_e32 v39, v39
	v_add_f32_e32 v176, v36, v176
	v_add_f32_e32 v177, v37, v177
	s_waitcnt lgkmcnt(10)
	v_mfma_f32_32x32x16_bf16 v[80:95], v[204:207], v[102:105], v[80:95]
	v_cvt_pk_bf16_f32 v34, v36, v37
	v_add_f32_e32 v176, v38, v176
	v_add_f32_e32 v177, v39, v177
	v_cvt_pk_bf16_f32 v35, v38, v39
	v_mfma_f32_32x32x16_bf16 v[64:79], v[208:211], v[102:105], v[64:79]
	v_exp_f32_e32 v40, v40
	v_exp_f32_e32 v41, v41
	v_exp_f32_e32 v42, v42
	v_exp_f32_e32 v43, v43
	s_waitcnt vmcnt(2)
	s_barrier
	s_waitcnt lgkmcnt(5)
	v_mfma_f32_32x32x16_bf16 v[0:15], v[32:35], v[220:223], v[0:15]
	ds_read_b128 v[196:199], v194 offset:0
	ds_read_b128 v[200:203], v194 offset:512
	ds_read_b128 v[204:207], v194 offset:2048
	ds_read_b128 v[208:211], v194 offset:2560
	ds_read_b64_tr_b16 v[220:221], v127 offset:20480
	ds_read_b64_tr_b16 v[222:223], v127 offset:20992
	v_add_f32_e32 v176, v40, v176
	v_add_f32_e32 v177, v41, v177
	v_cvt_pk_bf16_f32 v36, v40, v41
	v_add_f32_e32 v176, v42, v176
	v_mfma_f32_32x32x16_bf16 v[16:31], v[32:35], v[244:247], v[16:31]
	ds_read_b64_tr_b16 v[244:245], v127 offset:24576
	ds_read_b64_tr_b16 v[246:247], v127 offset:25088
	v_add_f32_e32 v177, v43, v177
	v_cvt_pk_bf16_f32 v37, v42, v43
	v_exp_f32_e32 v44, v44
	v_exp_f32_e32 v45, v45
	s_waitcnt lgkmcnt(12)
	v_mfma_f32_32x32x16_bf16 v[80:95], v[212:215], v[98:101], v[80:95]
	ds_read_b128 v[212:215], v194 offset:4096
	v_exp_f32_e32 v46, v46
	v_exp_f32_e32 v47, v47
	v_add_f32_e32 v176, v44, v176
	v_add_f32_e32 v177, v45, v177
	v_mfma_f32_32x32x16_bf16 v[64:79], v[216:219], v[98:101], v[64:79]
	ds_read_b128 v[216:219], v194 offset:4608
	v_cvt_pk_bf16_f32 v38, v44, v45
	v_add_f32_e32 v176, v46, v176
	v_add_f32_e32 v177, v47, v177
	v_cvt_pk_bf16_f32 v39, v46, v47
	s_waitcnt lgkmcnt(10)
	v_mfma_f32_32x32x16_bf16 v[0:15], v[36:39], v[240:243], v[0:15]
	v_add_f32_e32 v175, v176, v177
	v_mov_b32_e32 v178, v175
	v_add_f32_e32 v147, v147, v175
	s_nop 0
	v_mfma_f32_32x32x16_bf16 v[16:31], v[36:39], v[122:125], v[16:31]
	v_permlane32_swap_b32_e32 v175, v178
	v_add_f32_e32 v175, v175, v178
	v_cmp_lt_f32_e32 vcc, 0x43800000, v175
	s_cbranch_vccz .Lat_nr_10
	v_log_f32_e32 v175, v175
	s_nop 0
	v_max_f32_e32 v175, 0, v175
	v_exp_f32_e64 v178, -v175
	s_and_saveexec_b64 s[4:5], s[2:3]
	ds_write_b32 v143, v178 offset:40960
	s_or_b64 exec, exec, s[4:5]
	s_waitcnt lgkmcnt(0)
	v_add_u32_e32 v179, s33, v191
	v_sub_f32_e32 v224, v224, v175
	v_mul_f32_e32 v147, v147, v178
	ds_read_b128 v[48:51], v179 offset:40960
	ds_read_b128 v[52:55], v179 offset:40992
	ds_read_b128 v[56:59], v179 offset:41024
	ds_read_b128 v[60:63], v179 offset:41056
	s_waitcnt lgkmcnt(0)
	s_nop 15
	v_pk_mul_f32 v[0:1], v[0:1], v[48:49]
	v_pk_mul_f32 v[2:3], v[2:3], v[50:51]
	v_pk_mul_f32 v[4:5], v[4:5], v[52:53]
	v_pk_mul_f32 v[6:7], v[6:7], v[54:55]
	v_pk_mul_f32 v[8:9], v[8:9], v[56:57]
	v_pk_mul_f32 v[10:11], v[10:11], v[58:59]
	v_pk_mul_f32 v[12:13], v[12:13], v[60:61]
	v_pk_mul_f32 v[14:15], v[14:15], v[62:63]
	v_pk_mul_f32 v[16:17], v[16:17], v[48:49]
	v_pk_mul_f32 v[18:19], v[18:19], v[50:51]
	v_pk_mul_f32 v[20:21], v[20:21], v[52:53]
	v_pk_mul_f32 v[22:23], v[22:23], v[54:55]
	v_pk_mul_f32 v[24:25], v[24:25], v[56:57]
	v_pk_mul_f32 v[26:27], v[26:27], v[58:59]
	v_pk_mul_f32 v[28:29], v[28:29], v[60:61]
	v_pk_mul_f32 v[30:31], v[30:31], v[62:63]
	v_mov_b32_e32 v225, v224
	v_mov_b32_e32 v226, v224
	v_mov_b32_e32 v227, v224
	v_mov_b32_e32 v228, v224
	v_mov_b32_e32 v229, v224
	v_mov_b32_e32 v230, v224
	v_mov_b32_e32 v231, v224
	v_mov_b32_e32 v232, v224
	v_mov_b32_e32 v233, v224
	v_mov_b32_e32 v234, v224
	v_mov_b32_e32 v235, v224
	v_mov_b32_e32 v236, v224
	v_mov_b32_e32 v237, v224
	v_mov_b32_e32 v238, v224
	v_mov_b32_e32 v239, v224
	v_sub_f32_e32 v80, v80, v175
	v_sub_f32_e32 v81, v81, v175
	v_sub_f32_e32 v82, v82, v175
	v_sub_f32_e32 v83, v83, v175
	v_sub_f32_e32 v84, v84, v175
	v_sub_f32_e32 v85, v85, v175
	v_sub_f32_e32 v86, v86, v175
	v_sub_f32_e32 v87, v87, v175
	v_sub_f32_e32 v88, v88, v175
	v_sub_f32_e32 v89, v89, v175
	v_sub_f32_e32 v90, v90, v175
	v_sub_f32_e32 v91, v91, v175
	v_sub_f32_e32 v92, v92, v175
	v_sub_f32_e32 v93, v93, v175
	v_sub_f32_e32 v94, v94, v175
	v_sub_f32_e32 v95, v95, v175
	v_sub_f32_e32 v64, v64, v175
	v_sub_f32_e32 v65, v65, v175
	v_sub_f32_e32 v66, v66, v175
	v_sub_f32_e32 v67, v67, v175
	v_sub_f32_e32 v68, v68, v175
	v_sub_f32_e32 v69, v69, v175
	v_sub_f32_e32 v70, v70, v175
	v_sub_f32_e32 v71, v71, v175
	v_sub_f32_e32 v72, v72, v175
	v_sub_f32_e32 v73, v73, v175
	v_sub_f32_e32 v74, v74, v175
	v_sub_f32_e32 v75, v75, v175
	v_sub_f32_e32 v76, v76, v175
	v_sub_f32_e32 v77, v77, v175
	v_sub_f32_e32 v78, v78, v175
	v_sub_f32_e32 v79, v79, v175

.Lat_k2_11:
	s_add_u32 s12, s12, 0x30000
	s_addc_u32 s13, s13, 0
	s_add_i32 m0, s22, 0x8000
	s_nop 0
	global_load_lds_dwordx4 v145, s[14:15]
	s_add_u32 s14, s14, 0x20000
	s_addc_u32 s15, s15, 0
	v_exp_f32_e32 v80, v80
	v_exp_f32_e32 v81, v81
	v_exp_f32_e32 v82, v82
	v_exp_f32_e32 v83, v83
	v_mov_b32_e32 v176, v80
	v_mov_b32_e32 v177, v81
	v_cvt_pk_bf16_f32 v80, v80, v81
	v_add_f32_e32 v176, v82, v176
	s_waitcnt lgkmcnt(8)
	v_mfma_f32_32x32x16_bf16 v[48:63], v[196:199], v[110:113], v[224:239]
	ds_read_b128 v[196:199], v194 offset:6144
	ds_read_b64_tr_b16 v[240:241], v127 offset:21504
	ds_read_b64_tr_b16 v[242:243], v127 offset:22016
	v_add_f32_e32 v177, v83, v177
	v_cvt_pk_bf16_f32 v81, v82, v83
	v_exp_f32_e32 v84, v84
	v_exp_f32_e32 v85, v85
	v_mfma_f32_32x32x16_bf16 v[32:47], v[200:203], v[110:113], v[224:239]
	ds_read_b128 v[200:203], v194 offset:6656
	ds_read_b64_tr_b16 v[122:123], v127 offset:25600
	ds_read_b64_tr_b16 v[124:125], v127 offset:26112
	v_exp_f32_e32 v86, v86
	v_exp_f32_e32 v87, v87
	v_add_f32_e32 v176, v84, v176
	v_add_f32_e32 v177, v85, v177
	s_waitcnt lgkmcnt(12)
	v_mfma_f32_32x32x16_bf16 v[48:63], v[204:207], v[106:109], v[48:63]
	ds_read_b128 v[204:207], v194 offset:8192
	v_cvt_pk_bf16_f32 v82, v84, v85
	v_add_f32_e32 v176, v86, v176
	v_add_f32_e32 v177, v87, v177
	v_cvt_pk_bf16_f32 v83, v86, v87
	v_mfma_f32_32x32x16_bf16 v[32:47], v[208:211], v[106:109], v[32:47]
	ds_read_b128 v[208:211], v194 offset:8704
	v_exp_f32_e32 v88, v88
	v_exp_f32_e32 v89, v89
	v_exp_f32_e32 v90, v90
	v_exp_f32_e32 v91, v91
	s_waitcnt lgkmcnt(8)
	v_mfma_f32_32x32x16_bf16 v[48:63], v[212:215], v[114:117], v[48:63]
	ds_read_b128 v[212:215], v194 offset:10240
	v_add_f32_e32 v176, v88, v176
	v_add_f32_e32 v177, v89, v177
	v_cvt_pk_bf16_f32 v84, v88, v89
	v_add_f32_e32 v176, v90, v176
	v_mfma_f32_32x32x16_bf16 v[0:15], v[80:83], v[220:223], v[0:15]
	ds_read_b64_tr_b16 v[220:221], v127 offset:22528
	ds_read_b64_tr_b16 v[222:223], v127 offset:23040
	v_add_f32_e32 v177, v91, v177
	v_cvt_pk_bf16_f32 v85, v90, v91
	v_exp_f32_e32 v92, v92
	v_exp_f32_e32 v93, v93
	v_mfma_f32_32x32x16_bf16 v[16:31], v[80:83], v[244:247], v[16:31]
	ds_read_b64_tr_b16 v[244:245], v127 offset:26624
	ds_read_b64_tr_b16 v[246:247], v127 offset:27136
	v_exp_f32_e32 v94, v94
	v_exp_f32_e32 v95, v95
	v_add_f32_e32 v176, v92, v176
	v_add_f32_e32 v177, v93, v177
	v_mfma_f32_32x32x16_bf16 v[32:47], v[216:219], v[114:117], v[32:47]
	ds_read_b128 v[216:219], v194 offset:10752
	v_cvt_pk_bf16_f32 v86, v92, v93
	v_add_f32_e32 v176, v94, v176
	v_add_f32_e32 v177, v95, v177
	v_cvt_pk_bf16_f32 v87, v94, v95
	s_waitcnt lgkmcnt(10)
	v_mfma_f32_32x32x16_bf16 v[48:63], v[196:199], v[118:121], v[48:63]
	v_exp_f32_e32 v64, v64
	v_exp_f32_e32 v65, v65
	v_exp_f32_e32 v66, v66
	v_exp_f32_e32 v67, v67
	v_mfma_f32_32x32x16_bf16 v[32:47], v[200:203], v[118:121], v[32:47]
	v_add_f32_e32 v176, v64, v176
	v_add_f32_e32 v177, v65, v177
	v_cvt_pk_bf16_f32 v64, v64, v65
	v_add_f32_e32 v176, v66, v176
	s_waitcnt lgkmcnt(8)
	v_mfma_f32_32x32x16_bf16 v[0:15], v[84:87], v[240:243], v[0:15]
	ds_read_b64_tr_b16 v[240:241], v127 offset:23552
	ds_read_b64_tr_b16 v[242:243], v127 offset:24064
	v_add_f32_e32 v177, v67, v177
	v_cvt_pk_bf16_f32 v65, v66, v67
	v_exp_f32_e32 v68, v68
	v_exp_f32_e32 v69, v69
	v_mfma_f32_32x32x16_bf16 v[16:31], v[84:87], v[122:125], v[16:31]
	ds_read_b64_tr_b16 v[122:123], v127 offset:27648
	ds_read_b64_tr_b16 v[124:125], v127 offset:28160
	v_exp_f32_e32 v70, v70
	v_exp_f32_e32 v71, v71
	v_add_f32_e32 v176, v68, v176
	v_add_f32_e32 v177, v69, v177
	s_waitcnt lgkmcnt(10)
	v_mfma_f32_32x32x16_bf16 v[48:63], v[204:207], v[102:105], v[48:63]
	v_cvt_pk_bf16_f32 v66, v68, v69
	v_add_f32_e32 v176, v70, v176
	v_add_f32_e32 v177, v71, v177
	v_cvt_pk_bf16_f32 v67, v70, v71
	v_mfma_f32_32x32x16_bf16 v[32:47], v[208:211], v[102:105], v[32:47]
	v_exp_f32_e32 v72, v72
	v_exp_f32_e32 v73, v73
	v_exp_f32_e32 v74, v74
	v_exp_f32_e32 v75, v75
	s_waitcnt vmcnt(2)
	s_barrier
	s_waitcnt lgkmcnt(5)
	v_mfma_f32_32x32x16_bf16 v[0:15], v[64:67], v[220:223], v[0:15]
	ds_read_b128 v[196:199], v194 offset:20480
	ds_read_b128 v[200:203], v194 offset:20992
	ds_read_b128 v[204:207], v194 offset:22528
	ds_read_b128 v[208:211], v194 offset:23040
	ds_read_b64_tr_b16 v[220:221], v139 offset:0
	ds_read_b64_tr_b16 v[222:223], v139 offset:512
	v_add_f32_e32 v176, v72, v176
	v_add_f32_e32 v177, v73, v177
	v_cvt_pk_bf16_f32 v68, v72, v73
	v_add_f32_e32 v176, v74, v176
	v_mfma_f32_32x32x16_bf16 v[16:31], v[64:67], v[244:247], v[16:31]
	ds_read_b64_tr_b16 v[244:245], v139 offset:4096
	ds_read_b64_tr_b16 v[246:247], v139 offset:4608
	v_add_f32_e32 v177, v75, v177
	v_cvt_pk_bf16_f32 v69, v74, v75
	v_exp_f32_e32 v76, v76
	v_exp_f32_e32 v77, v77
	s_waitcnt lgkmcnt(12)
	v_mfma_f32_32x32x16_bf16 v[48:63], v[212:215], v[98:101], v[48:63]
	ds_read_b128 v[212:215], v194 offset:24576
	v_exp_f32_e32 v78, v78
	v_exp_f32_e32 v79, v79
	v_add_f32_e32 v176, v76, v176
	v_add_f32_e32 v177, v77, v177
	v_mfma_f32_32x32x16_bf16 v[32:47], v[216:219], v[98:101], v[32:47]
	ds_read_b128 v[216:219], v194 offset:25088
	v_cvt_pk_bf16_f32 v70, v76, v77
	v_add_f32_e32 v176, v78, v176
	v_add_f32_e32 v177, v79, v177
	v_cvt_pk_bf16_f32 v71, v78, v79
	s_waitcnt lgkmcnt(10)
	v_mfma_f32_32x32x16_bf16 v[0:15], v[68:71], v[240:243], v[0:15]
	v_add_f32_e32 v175, v176, v177
	v_mov_b32_e32 v178, v175
	v_add_f32_e32 v147, v147, v175
	s_nop 0
	v_mfma_f32_32x32x16_bf16 v[16:31], v[68:71], v[122:125], v[16:31]
	v_permlane32_swap_b32_e32 v175, v178
	v_add_f32_e32 v175, v175, v178
	v_cmp_lt_f32_e32 vcc, 0x43800000, v175
	s_cbranch_vccz .Lat_nr_12
	v_log_f32_e32 v175, v175
	s_nop 0
	v_max_f32_e32 v175, 0, v175
	v_exp_f32_e64 v178, -v175
	s_and_saveexec_b64 s[4:5], s[2:3]
	ds_write_b32 v143, v178 offset:40960
	s_or_b64 exec, exec, s[4:5]
	s_waitcnt lgkmcnt(0)
	v_add_u32_e32 v179, s33, v191
	v_sub_f32_e32 v224, v224, v175
	v_mul_f32_e32 v147, v147, v178
	ds_read_b128 v[80:83], v179 offset:40960
	ds_read_b128 v[84:87], v179 offset:40992
	ds_read_b128 v[88:91], v179 offset:41024
	ds_read_b128 v[92:95], v179 offset:41056
	s_waitcnt lgkmcnt(0)
	s_nop 15
	v_pk_mul_f32 v[0:1], v[0:1], v[80:81]
	v_pk_mul_f32 v[2:3], v[2:3], v[82:83]
	v_pk_mul_f32 v[4:5], v[4:5], v[84:85]
	v_pk_mul_f32 v[6:7], v[6:7], v[86:87]
	v_pk_mul_f32 v[8:9], v[8:9], v[88:89]
	v_pk_mul_f32 v[10:11], v[10:11], v[90:91]
	v_pk_mul_f32 v[12:13], v[12:13], v[92:93]
	v_pk_mul_f32 v[14:15], v[14:15], v[94:95]
	v_pk_mul_f32 v[16:17], v[16:17], v[80:81]
	v_pk_mul_f32 v[18:19], v[18:19], v[82:83]
	v_pk_mul_f32 v[20:21], v[20:21], v[84:85]
	v_pk_mul_f32 v[22:23], v[22:23], v[86:87]
	v_pk_mul_f32 v[24:25], v[24:25], v[88:89]
	v_pk_mul_f32 v[26:27], v[26:27], v[90:91]
	v_pk_mul_f32 v[28:29], v[28:29], v[92:93]
	v_pk_mul_f32 v[30:31], v[30:31], v[94:95]
	v_mov_b32_e32 v225, v224
	v_mov_b32_e32 v226, v224
	v_mov_b32_e32 v227, v224
	v_mov_b32_e32 v228, v224
	v_mov_b32_e32 v229, v224
	v_mov_b32_e32 v230, v224
	v_mov_b32_e32 v231, v224
	v_mov_b32_e32 v232, v224
	v_mov_b32_e32 v233, v224
	v_mov_b32_e32 v234, v224
	v_mov_b32_e32 v235, v224
	v_mov_b32_e32 v236, v224
	v_mov_b32_e32 v237, v224
	v_mov_b32_e32 v238, v224
	v_mov_b32_e32 v239, v224
	v_sub_f32_e32 v48, v48, v175
	v_sub_f32_e32 v49, v49, v175
	v_sub_f32_e32 v50, v50, v175
	v_sub_f32_e32 v51, v51, v175
	v_sub_f32_e32 v52, v52, v175
	v_sub_f32_e32 v53, v53, v175
	v_sub_f32_e32 v54, v54, v175
	v_sub_f32_e32 v55, v55, v175
	v_sub_f32_e32 v56, v56, v175
	v_sub_f32_e32 v57, v57, v175
	v_sub_f32_e32 v58, v58, v175
	v_sub_f32_e32 v59, v59, v175
	v_sub_f32_e32 v60, v60, v175
	v_sub_f32_e32 v61, v61, v175
	v_sub_f32_e32 v62, v62, v175
	v_sub_f32_e32 v63, v63, v175
	v_sub_f32_e32 v32, v32, v175
	v_sub_f32_e32 v33, v33, v175
	v_sub_f32_e32 v34, v34, v175
	v_sub_f32_e32 v35, v35, v175
	v_sub_f32_e32 v36, v36, v175
	v_sub_f32_e32 v37, v37, v175
	v_sub_f32_e32 v38, v38, v175
	v_sub_f32_e32 v39, v39, v175
	v_sub_f32_e32 v40, v40, v175
	v_sub_f32_e32 v41, v41, v175
	v_sub_f32_e32 v42, v42, v175
	v_sub_f32_e32 v43, v43, v175
	v_sub_f32_e32 v44, v44, v175
	v_sub_f32_e32 v45, v45, v175
	v_sub_f32_e32 v46, v46, v175
	v_sub_f32_e32 v47, v47, v175

.Lat_k2_13:
	s_add_i32 m0, s22, 0x13000
	s_nop 0
	global_load_lds_dwordx4 v145, s[14:15]
	s_add_u32 s14, s14, 0x20000
	s_addc_u32 s15, s15, 0
	v_exp_f32_e32 v48, v48
	v_exp_f32_e32 v49, v49
	v_exp_f32_e32 v50, v50
	v_exp_f32_e32 v51, v51
	v_mov_b32_e32 v176, v48
	v_mov_b32_e32 v177, v49
	v_cvt_pk_bf16_f32 v48, v48, v49
	v_add_f32_e32 v176, v50, v176
	s_waitcnt lgkmcnt(8)
	v_mfma_f32_32x32x16_bf16 v[80:95], v[196:199], v[110:113], v[224:239]
	ds_read_b128 v[196:199], v194 offset:26624
	ds_read_b64_tr_b16 v[240:241], v139 offset:1024
	ds_read_b64_tr_b16 v[242:243], v139 offset:1536
	v_add_f32_e32 v177, v51, v177
	v_cvt_pk_bf16_f32 v49, v50, v51
	v_exp_f32_e32 v52, v52
	v_exp_f32_e32 v53, v53
	v_mfma_f32_32x32x16_bf16 v[64:79], v[200:203], v[110:113], v[224:239]
	ds_read_b128 v[200:203], v194 offset:27136
	ds_read_b64_tr_b16 v[122:123], v139 offset:5120
	ds_read_b64_tr_b16 v[124:125], v139 offset:5632
	v_exp_f32_e32 v54, v54
	v_exp_f32_e32 v55, v55
	v_add_f32_e32 v176, v52, v176
	v_add_f32_e32 v177, v53, v177
	s_waitcnt lgkmcnt(12)
	v_mfma_f32_32x32x16_bf16 v[80:95], v[204:207], v[106:109], v[80:95]
	ds_read_b128 v[204:207], v194 offset:28672
	v_cvt_pk_bf16_f32 v50, v52, v53
	v_add_f32_e32 v176, v54, v176
	v_add_f32_e32 v177, v55, v177
	v_cvt_pk_bf16_f32 v51, v54, v55
	v_mfma_f32_32x32x16_bf16 v[64:79], v[208:211], v[106:109], v[64:79]
	ds_read_b128 v[208:211], v194 offset:29184
	v_exp_f32_e32 v56, v56
	v_exp_f32_e32 v57, v57
	v_exp_f32_e32 v58, v58
	v_exp_f32_e32 v59, v59
	s_waitcnt lgkmcnt(8)
	v_mfma_f32_32x32x16_bf16 v[80:95], v[212:215], v[114:117], v[80:95]
	ds_read_b128 v[212:215], v194 offset:30720
	v_add_f32_e32 v176, v56, v176
	v_add_f32_e32 v177, v57, v177
	v_cvt_pk_bf16_f32 v52, v56, v57
	v_add_f32_e32 v176, v58, v176
	v_mfma_f32_32x32x16_bf16 v[0:15], v[48:51], v[220:223], v[0:15]
	ds_read_b64_tr_b16 v[220:221], v139 offset:2048
	ds_read_b64_tr_b16 v[222:223], v139 offset:2560
	v_add_f32_e32 v177, v59, v177
	v_cvt_pk_bf16_f32 v53, v58, v59
	v_exp_f32_e32 v60, v60
	v_exp_f32_e32 v61, v61
	v_mfma_f32_32x32x16_bf16 v[16:31], v[48:51], v[244:247], v[16:31]
	ds_read_b64_tr_b16 v[244:245], v139 offset:6144
	ds_read_b64_tr_b16 v[246:247], v139 offset:6656
	v_exp_f32_e32 v62, v62
	v_exp_f32_e32 v63, v63
	v_add_f32_e32 v176, v60, v176
	v_add_f32_e32 v177, v61, v177
	v_mfma_f32_32x32x16_bf16 v[64:79], v[216:219], v[114:117], v[64:79]
	ds_read_b128 v[216:219], v194 offset:31232
	v_cvt_pk_bf16_f32 v54, v60, v61
	v_add_f32_e32 v176, v62, v176
	v_add_f32_e32 v177, v63, v177
	v_cvt_pk_bf16_f32 v55, v62, v63
	s_waitcnt lgkmcnt(10)
	v_mfma_f32_32x32x16_bf16 v[80:95], v[196:199], v[118:121], v[80:95]
	v_exp_f32_e32 v32, v32
	v_exp_f32_e32 v33, v33
	v_exp_f32_e32 v34, v34
	v_exp_f32_e32 v35, v35
	v_mfma_f32_32x32x16_bf16 v[64:79], v[200:203], v[118:121], v[64:79]
	v_add_f32_e32 v176, v32, v176
	v_add_f32_e32 v177, v33, v177
	v_cvt_pk_bf16_f32 v32, v32, v33
	v_add_f32_e32 v176, v34, v176
	s_waitcnt lgkmcnt(8)
	v_mfma_f32_32x32x16_bf16 v[0:15], v[52:55], v[240:243], v[0:15]
	ds_read_b64_tr_b16 v[240:241], v139 offset:3072
	ds_read_b64_tr_b16 v[242:243], v139 offset:3584
	v_add_f32_e32 v177, v35, v177
	v_cvt_pk_bf16_f32 v33, v34, v35
	v_exp_f32_e32 v36, v36
	v_exp_f32_e32 v37, v37
	v_mfma_f32_32x32x16_bf16 v[16:31], v[52:55], v[122:125], v[16:31]
	ds_read_b64_tr_b16 v[122:123], v139 offset:7168
	ds_read_b64_tr_b16 v[124:125], v139 offset:7680
	v_exp_f32_e32 v38, v38
	v_exp_f32_e32 v39, v39
	v_add_f32_e32 v176, v36, v176
	v_add_f32_e32 v177, v37, v177
	s_waitcnt lgkmcnt(10)
	v_mfma_f32_32x32x16_bf16 v[80:95], v[204:207], v[102:105], v[80:95]
	v_cvt_pk_bf16_f32 v34, v36, v37
	v_add_f32_e32 v176, v38, v176
	v_add_f32_e32 v177, v39, v177
	v_cvt_pk_bf16_f32 v35, v38, v39
	v_mfma_f32_32x32x16_bf16 v[64:79], v[208:211], v[102:105], v[64:79]
	v_exp_f32_e32 v40, v40
	v_exp_f32_e32 v41, v41
	v_exp_f32_e32 v42, v42
	v_exp_f32_e32 v43, v43
	s_waitcnt vmcnt(2)
	s_barrier
	s_waitcnt lgkmcnt(5)
	v_mfma_f32_32x32x16_bf16 v[0:15], v[32:35], v[220:223], v[0:15]
	ds_read_b128 v[196:199], v126 offset:0
	ds_read_b128 v[200:203], v126 offset:512
	ds_read_b128 v[204:207], v126 offset:2048
	ds_read_b128 v[208:211], v126 offset:2560
	ds_read_b64_tr_b16 v[220:221], v139 offset:20480
	ds_read_b64_tr_b16 v[222:223], v139 offset:20992
	v_add_f32_e32 v176, v40, v176
	v_add_f32_e32 v177, v41, v177
	v_cvt_pk_bf16_f32 v36, v40, v41
	v_add_f32_e32 v176, v42, v176
	v_mfma_f32_32x32x16_bf16 v[16:31], v[32:35], v[244:247], v[16:31]
	ds_read_b64_tr_b16 v[244:245], v139 offset:24576
	ds_read_b64_tr_b16 v[246:247], v139 offset:25088
	v_add_f32_e32 v177, v43, v177
	v_cvt_pk_bf16_f32 v37, v42, v43
	v_exp_f32_e32 v44, v44
	v_exp_f32_e32 v45, v45
	s_waitcnt lgkmcnt(12)
	v_mfma_f32_32x32x16_bf16 v[80:95], v[212:215], v[98:101], v[80:95]
	ds_read_b128 v[212:215], v126 offset:4096
	v_exp_f32_e32 v46, v46
	v_exp_f32_e32 v47, v47
	v_add_f32_e32 v176, v44, v176
	v_add_f32_e32 v177, v45, v177
	v_mfma_f32_32x32x16_bf16 v[64:79], v[216:219], v[98:101], v[64:79]
	ds_read_b128 v[216:219], v126 offset:4608
	v_cvt_pk_bf16_f32 v38, v44, v45
	v_add_f32_e32 v176, v46, v176
	v_add_f32_e32 v177, v47, v177
	v_cvt_pk_bf16_f32 v39, v46, v47
	s_waitcnt lgkmcnt(10)
	v_mfma_f32_32x32x16_bf16 v[0:15], v[36:39], v[240:243], v[0:15]
	v_add_f32_e32 v175, v176, v177
	v_mov_b32_e32 v178, v175
	v_add_f32_e32 v147, v147, v175
	s_nop 0
	v_mfma_f32_32x32x16_bf16 v[16:31], v[36:39], v[122:125], v[16:31]
	v_permlane32_swap_b32_e32 v175, v178
	v_add_f32_e32 v175, v175, v178
	v_cmp_lt_f32_e32 vcc, 0x43800000, v175
	s_cbranch_vccz .Lat_nr_14
	v_log_f32_e32 v175, v175
	s_nop 0
	v_max_f32_e32 v175, 0, v175
	v_exp_f32_e64 v178, -v175
	s_and_saveexec_b64 s[4:5], s[2:3]
	ds_write_b32 v143, v178 offset:40960
	s_or_b64 exec, exec, s[4:5]
	s_waitcnt lgkmcnt(0)
	v_add_u32_e32 v179, s33, v191
	v_sub_f32_e32 v224, v224, v175
	v_mul_f32_e32 v147, v147, v178
	ds_read_b128 v[48:51], v179 offset:40960
	ds_read_b128 v[52:55], v179 offset:40992
	ds_read_b128 v[56:59], v179 offset:41024
	ds_read_b128 v[60:63], v179 offset:41056
	s_waitcnt lgkmcnt(0)
	s_nop 15
	v_pk_mul_f32 v[0:1], v[0:1], v[48:49]
	v_pk_mul_f32 v[2:3], v[2:3], v[50:51]
	v_pk_mul_f32 v[4:5], v[4:5], v[52:53]
	v_pk_mul_f32 v[6:7], v[6:7], v[54:55]
	v_pk_mul_f32 v[8:9], v[8:9], v[56:57]
	v_pk_mul_f32 v[10:11], v[10:11], v[58:59]
	v_pk_mul_f32 v[12:13], v[12:13], v[60:61]
	v_pk_mul_f32 v[14:15], v[14:15], v[62:63]
	v_pk_mul_f32 v[16:17], v[16:17], v[48:49]
	v_pk_mul_f32 v[18:19], v[18:19], v[50:51]
	v_pk_mul_f32 v[20:21], v[20:21], v[52:53]
	v_pk_mul_f32 v[22:23], v[22:23], v[54:55]
	v_pk_mul_f32 v[24:25], v[24:25], v[56:57]
	v_pk_mul_f32 v[26:27], v[26:27], v[58:59]
	v_pk_mul_f32 v[28:29], v[28:29], v[60:61]
	v_pk_mul_f32 v[30:31], v[30:31], v[62:63]
	v_mov_b32_e32 v225, v224
	v_mov_b32_e32 v226, v224
	v_mov_b32_e32 v227, v224
	v_mov_b32_e32 v228, v224
	v_mov_b32_e32 v229, v224
	v_mov_b32_e32 v230, v224
	v_mov_b32_e32 v231, v224
	v_mov_b32_e32 v232, v224
	v_mov_b32_e32 v233, v224
	v_mov_b32_e32 v234, v224
	v_mov_b32_e32 v235, v224
	v_mov_b32_e32 v236, v224
	v_mov_b32_e32 v237, v224
	v_mov_b32_e32 v238, v224
	v_mov_b32_e32 v239, v224
	v_sub_f32_e32 v80, v80, v175
	v_sub_f32_e32 v81, v81, v175
	v_sub_f32_e32 v82, v82, v175
	v_sub_f32_e32 v83, v83, v175
	v_sub_f32_e32 v84, v84, v175
	v_sub_f32_e32 v85, v85, v175
	v_sub_f32_e32 v86, v86, v175
	v_sub_f32_e32 v87, v87, v175
	v_sub_f32_e32 v88, v88, v175
	v_sub_f32_e32 v89, v89, v175
	v_sub_f32_e32 v90, v90, v175
	v_sub_f32_e32 v91, v91, v175
	v_sub_f32_e32 v92, v92, v175
	v_sub_f32_e32 v93, v93, v175
	v_sub_f32_e32 v94, v94, v175
	v_sub_f32_e32 v95, v95, v175
	v_sub_f32_e32 v64, v64, v175
	v_sub_f32_e32 v65, v65, v175
	v_sub_f32_e32 v66, v66, v175
	v_sub_f32_e32 v67, v67, v175
	v_sub_f32_e32 v68, v68, v175
	v_sub_f32_e32 v69, v69, v175
	v_sub_f32_e32 v70, v70, v175
	v_sub_f32_e32 v71, v71, v175
	v_sub_f32_e32 v72, v72, v175
	v_sub_f32_e32 v73, v73, v175
	v_sub_f32_e32 v74, v74, v175
	v_sub_f32_e32 v75, v75, v175
	v_sub_f32_e32 v76, v76, v175
	v_sub_f32_e32 v77, v77, v175
	v_sub_f32_e32 v78, v78, v175
	v_sub_f32_e32 v79, v79, v175

.Lat_k2_15:
	s_add_u32 s12, s12, 0x30000
	s_addc_u32 s13, s13, 0
	s_add_i32 m0, s22, 0x18000
	s_nop 0
	global_load_lds_dwordx4 v145, s[14:15]
	v_exp_f32_e32 v80, v80
	v_exp_f32_e32 v81, v81
	v_exp_f32_e32 v82, v82
	v_exp_f32_e32 v83, v83
	v_mov_b32_e32 v176, v80
	v_mov_b32_e32 v177, v81
	v_cvt_pk_bf16_f32 v80, v80, v81
	v_add_f32_e32 v176, v82, v176
	s_waitcnt lgkmcnt(8)
	v_mfma_f32_32x32x16_bf16 v[48:63], v[196:199], v[110:113], v[224:239]
	ds_read_b128 v[196:199], v126 offset:6144
	ds_read_b64_tr_b16 v[240:241], v139 offset:21504
	ds_read_b64_tr_b16 v[242:243], v139 offset:22016
	v_add_f32_e32 v177, v83, v177
	v_cvt_pk_bf16_f32 v81, v82, v83
	v_exp_f32_e32 v84, v84
	v_exp_f32_e32 v85, v85
	v_mfma_f32_32x32x16_bf16 v[32:47], v[200:203], v[110:113], v[224:239]
	ds_read_b128 v[200:203], v126 offset:6656
	ds_read_b64_tr_b16 v[122:123], v139 offset:25600
	ds_read_b64_tr_b16 v[124:125], v139 offset:26112
	v_exp_f32_e32 v86, v86
	v_exp_f32_e32 v87, v87
	v_add_f32_e32 v176, v84, v176
	v_add_f32_e32 v177, v85, v177
	s_waitcnt lgkmcnt(12)
	v_mfma_f32_32x32x16_bf16 v[48:63], v[204:207], v[106:109], v[48:63]
	ds_read_b128 v[204:207], v126 offset:8192
	v_cvt_pk_bf16_f32 v82, v84, v85
	v_add_f32_e32 v176, v86, v176
	v_add_f32_e32 v177, v87, v177
	v_cvt_pk_bf16_f32 v83, v86, v87
	v_mfma_f32_32x32x16_bf16 v[32:47], v[208:211], v[106:109], v[32:47]
	ds_read_b128 v[208:211], v126 offset:8704
	v_exp_f32_e32 v88, v88
	v_exp_f32_e32 v89, v89
	v_exp_f32_e32 v90, v90
	v_exp_f32_e32 v91, v91
	s_waitcnt lgkmcnt(8)
	v_mfma_f32_32x32x16_bf16 v[48:63], v[212:215], v[114:117], v[48:63]
	ds_read_b128 v[212:215], v126 offset:10240
	v_add_f32_e32 v176, v88, v176
	v_add_f32_e32 v177, v89, v177
	v_cvt_pk_bf16_f32 v84, v88, v89
	v_add_f32_e32 v176, v90, v176
	v_mfma_f32_32x32x16_bf16 v[0:15], v[80:83], v[220:223], v[0:15]
	ds_read_b64_tr_b16 v[220:221], v139 offset:22528
	ds_read_b64_tr_b16 v[222:223], v139 offset:23040
	v_add_f32_e32 v177, v91, v177
	v_cvt_pk_bf16_f32 v85, v90, v91
	v_exp_f32_e32 v92, v92
	v_exp_f32_e32 v93, v93
	v_mfma_f32_32x32x16_bf16 v[16:31], v[80:83], v[244:247], v[16:31]
	ds_read_b64_tr_b16 v[244:245], v139 offset:26624
	ds_read_b64_tr_b16 v[246:247], v139 offset:27136
	v_exp_f32_e32 v94, v94
	v_exp_f32_e32 v95, v95
	v_add_f32_e32 v176, v92, v176
	v_add_f32_e32 v177, v93, v177
	v_mfma_f32_32x32x16_bf16 v[32:47], v[216:219], v[114:117], v[32:47]
	ds_read_b128 v[216:219], v126 offset:10752
	v_cvt_pk_bf16_f32 v86, v92, v93
	v_add_f32_e32 v176, v94, v176
	v_add_f32_e32 v177, v95, v177
	v_cvt_pk_bf16_f32 v87, v94, v95
	s_waitcnt lgkmcnt(10)
	v_mfma_f32_32x32x16_bf16 v[48:63], v[196:199], v[118:121], v[48:63]
	v_exp_f32_e32 v64, v64
	v_exp_f32_e32 v65, v65
	v_exp_f32_e32 v66, v66
	v_exp_f32_e32 v67, v67
	v_mfma_f32_32x32x16_bf16 v[32:47], v[200:203], v[118:121], v[32:47]
	v_add_f32_e32 v176, v64, v176
	v_add_f32_e32 v177, v65, v177
	v_cvt_pk_bf16_f32 v64, v64, v65
	v_add_f32_e32 v176, v66, v176
	s_waitcnt lgkmcnt(8)
	v_mfma_f32_32x32x16_bf16 v[0:15], v[84:87], v[240:243], v[0:15]
	ds_read_b64_tr_b16 v[240:241], v139 offset:23552
	ds_read_b64_tr_b16 v[242:243], v139 offset:24064
	v_add_f32_e32 v177, v67, v177
	v_cvt_pk_bf16_f32 v65, v66, v67
	v_exp_f32_e32 v68, v68
	v_exp_f32_e32 v69, v69
	v_mfma_f32_32x32x16_bf16 v[16:31], v[84:87], v[122:125], v[16:31]
	ds_read_b64_tr_b16 v[122:123], v139 offset:27648
	ds_read_b64_tr_b16 v[124:125], v139 offset:28160
	v_exp_f32_e32 v70, v70
	v_exp_f32_e32 v71, v71
	v_add_f32_e32 v176, v68, v176
	v_add_f32_e32 v177, v69, v177
	s_waitcnt lgkmcnt(10)
	v_mfma_f32_32x32x16_bf16 v[48:63], v[204:207], v[102:105], v[48:63]
	v_cvt_pk_bf16_f32 v66, v68, v69
	v_add_f32_e32 v176, v70, v176
	v_add_f32_e32 v177, v71, v177
	v_cvt_pk_bf16_f32 v67, v70, v71
	v_mfma_f32_32x32x16_bf16 v[32:47], v[208:211], v[102:105], v[32:47]
	v_exp_f32_e32 v72, v72
	v_exp_f32_e32 v73, v73
	v_exp_f32_e32 v74, v74
	v_exp_f32_e32 v75, v75
	s_waitcnt vmcnt(2)
	s_barrier
	s_waitcnt lgkmcnt(5)
	v_mfma_f32_32x32x16_bf16 v[0:15], v[64:67], v[220:223], v[0:15]
	ds_read_b128 v[196:199], v126 offset:20480
	ds_read_b128 v[200:203], v126 offset:20992
	ds_read_b128 v[204:207], v126 offset:22528
	ds_read_b128 v[208:211], v126 offset:23040
	ds_read_b64_tr_b16 v[220:221], v127 offset:0
	ds_read_b64_tr_b16 v[222:223], v127 offset:512
	v_add_f32_e32 v176, v72, v176
	v_add_f32_e32 v177, v73, v177
	v_cvt_pk_bf16_f32 v68, v72, v73
	v_add_f32_e32 v176, v74, v176
	v_mfma_f32_32x32x16_bf16 v[16:31], v[64:67], v[244:247], v[16:31]
	ds_read_b64_tr_b16 v[244:245], v127 offset:4096
	ds_read_b64_tr_b16 v[246:247], v127 offset:4608
	v_add_f32_e32 v177, v75, v177
	v_cvt_pk_bf16_f32 v69, v74, v75
	v_exp_f32_e32 v76, v76
	v_exp_f32_e32 v77, v77
	s_waitcnt lgkmcnt(12)
	v_mfma_f32_32x32x16_bf16 v[48:63], v[212:215], v[98:101], v[48:63]
	ds_read_b128 v[212:215], v126 offset:24576
	v_exp_f32_e32 v78, v78
	v_exp_f32_e32 v79, v79
	v_add_f32_e32 v176, v76, v176
	v_add_f32_e32 v177, v77, v177
	v_mfma_f32_32x32x16_bf16 v[32:47], v[216:219], v[98:101], v[32:47]
	ds_read_b128 v[216:219], v126 offset:25088
	v_cvt_pk_bf16_f32 v70, v76, v77
	v_add_f32_e32 v176, v78, v176
	v_add_f32_e32 v177, v79, v177
	v_cvt_pk_bf16_f32 v71, v78, v79
	s_waitcnt lgkmcnt(10)
	v_mfma_f32_32x32x16_bf16 v[0:15], v[68:71], v[240:243], v[0:15]
	v_add_f32_e32 v175, v176, v177
	v_mov_b32_e32 v178, v175
	v_add_f32_e32 v147, v147, v175
	s_nop 0
	v_mfma_f32_32x32x16_bf16 v[16:31], v[68:71], v[122:125], v[16:31]
	v_permlane32_swap_b32_e32 v175, v178
	v_add_f32_e32 v175, v175, v178
	v_cmp_lt_f32_e32 vcc, 0x43800000, v175
	s_cbranch_vccz .Lat_nr_16
	v_log_f32_e32 v175, v175
	s_nop 0
	v_max_f32_e32 v175, 0, v175
	v_exp_f32_e64 v178, -v175
	s_and_saveexec_b64 s[4:5], s[2:3]
	ds_write_b32 v143, v178 offset:40960
	s_or_b64 exec, exec, s[4:5]
	s_waitcnt lgkmcnt(0)
	v_add_u32_e32 v179, s33, v191
	v_sub_f32_e32 v224, v224, v175
	v_mul_f32_e32 v147, v147, v178
	ds_read_b128 v[80:83], v179 offset:40960
	ds_read_b128 v[84:87], v179 offset:40992
	ds_read_b128 v[88:91], v179 offset:41024
	ds_read_b128 v[92:95], v179 offset:41056
	s_waitcnt lgkmcnt(0)
	s_nop 15
	v_pk_mul_f32 v[0:1], v[0:1], v[80:81]
	v_pk_mul_f32 v[2:3], v[2:3], v[82:83]
	v_pk_mul_f32 v[4:5], v[4:5], v[84:85]
	v_pk_mul_f32 v[6:7], v[6:7], v[86:87]
	v_pk_mul_f32 v[8:9], v[8:9], v[88:89]
	v_pk_mul_f32 v[10:11], v[10:11], v[90:91]
	v_pk_mul_f32 v[12:13], v[12:13], v[92:93]
	v_pk_mul_f32 v[14:15], v[14:15], v[94:95]
	v_pk_mul_f32 v[16:17], v[16:17], v[80:81]
	v_pk_mul_f32 v[18:19], v[18:19], v[82:83]
	v_pk_mul_f32 v[20:21], v[20:21], v[84:85]
	v_pk_mul_f32 v[22:23], v[22:23], v[86:87]
	v_pk_mul_f32 v[24:25], v[24:25], v[88:89]
	v_pk_mul_f32 v[26:27], v[26:27], v[90:91]
	v_pk_mul_f32 v[28:29], v[28:29], v[92:93]
	v_pk_mul_f32 v[30:31], v[30:31], v[94:95]
	v_mov_b32_e32 v225, v224
	v_mov_b32_e32 v226, v224
	v_mov_b32_e32 v227, v224
	v_mov_b32_e32 v228, v224
	v_mov_b32_e32 v229, v224
	v_mov_b32_e32 v230, v224
	v_mov_b32_e32 v231, v224
	v_mov_b32_e32 v232, v224
	v_mov_b32_e32 v233, v224
	v_mov_b32_e32 v234, v224
	v_mov_b32_e32 v235, v224
	v_mov_b32_e32 v236, v224
	v_mov_b32_e32 v237, v224
	v_mov_b32_e32 v238, v224
	v_mov_b32_e32 v239, v224
	v_sub_f32_e32 v48, v48, v175
	v_sub_f32_e32 v49, v49, v175
	v_sub_f32_e32 v50, v50, v175
	v_sub_f32_e32 v51, v51, v175
	v_sub_f32_e32 v52, v52, v175
	v_sub_f32_e32 v53, v53, v175
	v_sub_f32_e32 v54, v54, v175
	v_sub_f32_e32 v55, v55, v175
	v_sub_f32_e32 v56, v56, v175
	v_sub_f32_e32 v57, v57, v175
	v_sub_f32_e32 v58, v58, v175
	v_sub_f32_e32 v59, v59, v175
	v_sub_f32_e32 v60, v60, v175
	v_sub_f32_e32 v61, v61, v175
	v_sub_f32_e32 v62, v62, v175
	v_sub_f32_e32 v63, v63, v175
	v_sub_f32_e32 v32, v32, v175
	v_sub_f32_e32 v33, v33, v175
	v_sub_f32_e32 v34, v34, v175
	v_sub_f32_e32 v35, v35, v175
	v_sub_f32_e32 v36, v36, v175
	v_sub_f32_e32 v37, v37, v175
	v_sub_f32_e32 v38, v38, v175
	v_sub_f32_e32 v39, v39, v175
	v_sub_f32_e32 v40, v40, v175
	v_sub_f32_e32 v41, v41, v175
	v_sub_f32_e32 v42, v42, v175
	v_sub_f32_e32 v43, v43, v175
	v_sub_f32_e32 v44, v44, v175
	v_sub_f32_e32 v45, v45, v175
	v_sub_f32_e32 v46, v46, v175
	v_sub_f32_e32 v47, v47, v175

.Lat_k2_17:
	s_add_u32 s12, s12, 0x30000
	s_addc_u32 s13, s13, 0
	s_mov_b64 s[14:15], s[38:39]
	s_add_i32 m0, s22, 0x3000
	s_nop 0
	global_load_lds_dwordx4 v145, s[14:15]
	s_add_u32 s14, s14, 0x20000
	s_addc_u32 s15, s15, 0
	v_exp_f32_e32 v48, v48
	v_exp_f32_e32 v49, v49
	v_exp_f32_e32 v50, v50
	v_exp_f32_e32 v51, v51
	v_mov_b32_e32 v176, v48
	v_mov_b32_e32 v177, v49
	v_cvt_pk_bf16_f32 v48, v48, v49
	v_add_f32_e32 v176, v50, v176
	s_waitcnt lgkmcnt(8)
	v_mfma_f32_32x32x16_bf16 v[80:95], v[196:199], v[110:113], v[224:239]
	ds_read_b128 v[196:199], v126 offset:26624
	ds_read_b64_tr_b16 v[240:241], v127 offset:1024
	ds_read_b64_tr_b16 v[242:243], v127 offset:1536
	v_add_f32_e32 v177, v51, v177
	v_cvt_pk_bf16_f32 v49, v50, v51
	v_exp_f32_e32 v52, v52
	v_exp_f32_e32 v53, v53
	v_mfma_f32_32x32x16_bf16 v[64:79], v[200:203], v[110:113], v[224:239]
	ds_read_b128 v[200:203], v126 offset:27136
	ds_read_b64_tr_b16 v[122:123], v127 offset:5120
	ds_read_b64_tr_b16 v[124:125], v127 offset:5632
	v_exp_f32_e32 v54, v54
	v_exp_f32_e32 v55, v55
	v_add_f32_e32 v176, v52, v176
	v_add_f32_e32 v177, v53, v177
	s_waitcnt lgkmcnt(12)
	v_mfma_f32_32x32x16_bf16 v[80:95], v[204:207], v[106:109], v[80:95]
	ds_read_b128 v[204:207], v126 offset:28672
	v_cvt_pk_bf16_f32 v50, v52, v53
	v_add_f32_e32 v176, v54, v176
	v_add_f32_e32 v177, v55, v177
	v_cvt_pk_bf16_f32 v51, v54, v55
	v_mfma_f32_32x32x16_bf16 v[64:79], v[208:211], v[106:109], v[64:79]
	ds_read_b128 v[208:211], v126 offset:29184
	v_exp_f32_e32 v56, v56
	v_exp_f32_e32 v57, v57
	v_exp_f32_e32 v58, v58
	v_exp_f32_e32 v59, v59
	s_waitcnt lgkmcnt(8)
	v_mfma_f32_32x32x16_bf16 v[80:95], v[212:215], v[114:117], v[80:95]
	ds_read_b128 v[212:215], v126 offset:30720
	v_add_f32_e32 v176, v56, v176
	v_add_f32_e32 v177, v57, v177
	v_cvt_pk_bf16_f32 v52, v56, v57
	v_add_f32_e32 v176, v58, v176
	v_mfma_f32_32x32x16_bf16 v[0:15], v[48:51], v[220:223], v[0:15]
	ds_read_b64_tr_b16 v[220:221], v127 offset:2048
	ds_read_b64_tr_b16 v[222:223], v127 offset:2560
	v_add_f32_e32 v177, v59, v177
	v_cvt_pk_bf16_f32 v53, v58, v59
	v_exp_f32_e32 v60, v60
	v_exp_f32_e32 v61, v61
	v_mfma_f32_32x32x16_bf16 v[16:31], v[48:51], v[244:247], v[16:31]
	ds_read_b64_tr_b16 v[244:245], v127 offset:6144
	ds_read_b64_tr_b16 v[246:247], v127 offset:6656
	v_exp_f32_e32 v62, v62
	v_exp_f32_e32 v63, v63
	v_add_f32_e32 v176, v60, v176
	v_add_f32_e32 v177, v61, v177
	v_mfma_f32_32x32x16_bf16 v[64:79], v[216:219], v[114:117], v[64:79]
	ds_read_b128 v[216:219], v126 offset:31232
	v_cvt_pk_bf16_f32 v54, v60, v61
	v_add_f32_e32 v176, v62, v176
	v_add_f32_e32 v177, v63, v177
	v_cvt_pk_bf16_f32 v55, v62, v63
	s_waitcnt lgkmcnt(10)
	v_mfma_f32_32x32x16_bf16 v[80:95], v[196:199], v[118:121], v[80:95]
	v_exp_f32_e32 v32, v32
	v_exp_f32_e32 v33, v33
	v_exp_f32_e32 v34, v34
	v_exp_f32_e32 v35, v35
	v_mfma_f32_32x32x16_bf16 v[64:79], v[200:203], v[118:121], v[64:79]
	v_add_f32_e32 v176, v32, v176
	v_add_f32_e32 v177, v33, v177
	v_cvt_pk_bf16_f32 v32, v32, v33
	v_add_f32_e32 v176, v34, v176
	s_waitcnt lgkmcnt(8)
	v_mfma_f32_32x32x16_bf16 v[0:15], v[52:55], v[240:243], v[0:15]
	ds_read_b64_tr_b16 v[240:241], v127 offset:3072
	ds_read_b64_tr_b16 v[242:243], v127 offset:3584
	v_add_f32_e32 v177, v35, v177
	v_cvt_pk_bf16_f32 v33, v34, v35
	v_exp_f32_e32 v36, v36
	v_exp_f32_e32 v37, v37
	v_mfma_f32_32x32x16_bf16 v[16:31], v[52:55], v[122:125], v[16:31]
	ds_read_b64_tr_b16 v[122:123], v127 offset:7168
	ds_read_b64_tr_b16 v[124:125], v127 offset:7680
	v_exp_f32_e32 v38, v38
	v_exp_f32_e32 v39, v39
	v_add_f32_e32 v176, v36, v176
	v_add_f32_e32 v177, v37, v177
	s_waitcnt lgkmcnt(10)
	v_mfma_f32_32x32x16_bf16 v[80:95], v[204:207], v[102:105], v[80:95]
	v_cvt_pk_bf16_f32 v34, v36, v37
	v_add_f32_e32 v176, v38, v176
	v_add_f32_e32 v177, v39, v177
	v_cvt_pk_bf16_f32 v35, v38, v39
	v_mfma_f32_32x32x16_bf16 v[64:79], v[208:211], v[102:105], v[64:79]
	v_exp_f32_e32 v40, v40
	v_exp_f32_e32 v41, v41
	v_exp_f32_e32 v42, v42
	v_exp_f32_e32 v43, v43
	s_waitcnt vmcnt(2)
	s_barrier
	s_waitcnt lgkmcnt(5)
	v_mfma_f32_32x32x16_bf16 v[0:15], v[32:35], v[220:223], v[0:15]
	ds_read_b128 v[196:199], v194 offset:0
	ds_read_b128 v[200:203], v194 offset:512
	ds_read_b128 v[204:207], v194 offset:2048
	ds_read_b128 v[208:211], v194 offset:2560
	ds_read_b64_tr_b16 v[220:221], v127 offset:20480
	ds_read_b64_tr_b16 v[222:223], v127 offset:20992
	v_add_f32_e32 v176, v40, v176
	v_add_f32_e32 v177, v41, v177
	v_cvt_pk_bf16_f32 v36, v40, v41
	v_add_f32_e32 v176, v42, v176
	v_mfma_f32_32x32x16_bf16 v[16:31], v[32:35], v[244:247], v[16:31]
	ds_read_b64_tr_b16 v[244:245], v127 offset:24576
	ds_read_b64_tr_b16 v[246:247], v127 offset:25088
	v_add_f32_e32 v177, v43, v177
	v_cvt_pk_bf16_f32 v37, v42, v43
	v_exp_f32_e32 v44, v44
	v_exp_f32_e32 v45, v45
	s_waitcnt lgkmcnt(12)
	v_mfma_f32_32x32x16_bf16 v[80:95], v[212:215], v[98:101], v[80:95]
	ds_read_b128 v[212:215], v194 offset:4096
	v_exp_f32_e32 v46, v46
	v_exp_f32_e32 v47, v47
	v_add_f32_e32 v176, v44, v176
	v_add_f32_e32 v177, v45, v177
	v_mfma_f32_32x32x16_bf16 v[64:79], v[216:219], v[98:101], v[64:79]
	ds_read_b128 v[216:219], v194 offset:4608
	v_cvt_pk_bf16_f32 v38, v44, v45
	v_add_f32_e32 v176, v46, v176
	v_add_f32_e32 v177, v47, v177
	v_cvt_pk_bf16_f32 v39, v46, v47
	s_waitcnt lgkmcnt(10)
	v_mfma_f32_32x32x16_bf16 v[0:15], v[36:39], v[240:243], v[0:15]
	v_add_f32_e32 v175, v176, v177
	v_mov_b32_e32 v178, v175
	v_add_f32_e32 v147, v147, v175
	s_nop 0
	v_mfma_f32_32x32x16_bf16 v[16:31], v[36:39], v[122:125], v[16:31]
	v_permlane32_swap_b32_e32 v175, v178
	v_add_f32_e32 v175, v175, v178
	v_cmp_lt_f32_e32 vcc, 0x43800000, v175
	s_cbranch_vccz .Lat_nr_18
	v_log_f32_e32 v175, v175
	s_nop 0
	v_max_f32_e32 v175, 0, v175
	v_exp_f32_e64 v178, -v175
	s_and_saveexec_b64 s[4:5], s[2:3]
	ds_write_b32 v143, v178 offset:40960
	s_or_b64 exec, exec, s[4:5]
	s_waitcnt lgkmcnt(0)
	v_add_u32_e32 v179, s33, v191
	v_sub_f32_e32 v224, v224, v175
	v_mul_f32_e32 v147, v147, v178
	ds_read_b128 v[48:51], v179 offset:40960
	ds_read_b128 v[52:55], v179 offset:40992
	ds_read_b128 v[56:59], v179 offset:41024
	ds_read_b128 v[60:63], v179 offset:41056
	s_waitcnt lgkmcnt(0)
	s_nop 15
	v_pk_mul_f32 v[0:1], v[0:1], v[48:49]
	v_pk_mul_f32 v[2:3], v[2:3], v[50:51]
	v_pk_mul_f32 v[4:5], v[4:5], v[52:53]
	v_pk_mul_f32 v[6:7], v[6:7], v[54:55]
	v_pk_mul_f32 v[8:9], v[8:9], v[56:57]
	v_pk_mul_f32 v[10:11], v[10:11], v[58:59]
	v_pk_mul_f32 v[12:13], v[12:13], v[60:61]
	v_pk_mul_f32 v[14:15], v[14:15], v[62:63]
	v_pk_mul_f32 v[16:17], v[16:17], v[48:49]
	v_pk_mul_f32 v[18:19], v[18:19], v[50:51]
	v_pk_mul_f32 v[20:21], v[20:21], v[52:53]
	v_pk_mul_f32 v[22:23], v[22:23], v[54:55]
	v_pk_mul_f32 v[24:25], v[24:25], v[56:57]
	v_pk_mul_f32 v[26:27], v[26:27], v[58:59]
	v_pk_mul_f32 v[28:29], v[28:29], v[60:61]
	v_pk_mul_f32 v[30:31], v[30:31], v[62:63]
	v_mov_b32_e32 v225, v224
	v_mov_b32_e32 v226, v224
	v_mov_b32_e32 v227, v224
	v_mov_b32_e32 v228, v224
	v_mov_b32_e32 v229, v224
	v_mov_b32_e32 v230, v224
	v_mov_b32_e32 v231, v224
	v_mov_b32_e32 v232, v224
	v_mov_b32_e32 v233, v224
	v_mov_b32_e32 v234, v224
	v_mov_b32_e32 v235, v224
	v_mov_b32_e32 v236, v224
	v_mov_b32_e32 v237, v224
	v_mov_b32_e32 v238, v224
	v_mov_b32_e32 v239, v224
	v_sub_f32_e32 v80, v80, v175
	v_sub_f32_e32 v81, v81, v175
	v_sub_f32_e32 v82, v82, v175
	v_sub_f32_e32 v83, v83, v175
	v_sub_f32_e32 v84, v84, v175
	v_sub_f32_e32 v85, v85, v175
	v_sub_f32_e32 v86, v86, v175
	v_sub_f32_e32 v87, v87, v175
	v_sub_f32_e32 v88, v88, v175
	v_sub_f32_e32 v89, v89, v175
	v_sub_f32_e32 v90, v90, v175
	v_sub_f32_e32 v91, v91, v175
	v_sub_f32_e32 v92, v92, v175
	v_sub_f32_e32 v93, v93, v175
	v_sub_f32_e32 v94, v94, v175
	v_sub_f32_e32 v95, v95, v175
	v_sub_f32_e32 v64, v64, v175
	v_sub_f32_e32 v65, v65, v175
	v_sub_f32_e32 v66, v66, v175
	v_sub_f32_e32 v67, v67, v175
	v_sub_f32_e32 v68, v68, v175
	v_sub_f32_e32 v69, v69, v175
	v_sub_f32_e32 v70, v70, v175
	v_sub_f32_e32 v71, v71, v175
	v_sub_f32_e32 v72, v72, v175
	v_sub_f32_e32 v73, v73, v175
	v_sub_f32_e32 v74, v74, v175
	v_sub_f32_e32 v75, v75, v175
	v_sub_f32_e32 v76, v76, v175
	v_sub_f32_e32 v77, v77, v175
	v_sub_f32_e32 v78, v78, v175
	v_sub_f32_e32 v79, v79, v175

.Lat_nr_22:
	s_add_i32 m0, s22, 0x18000
	s_nop 0
	global_load_lds_dwordx4 v145, s[14:15]
	v_exp_f32_e32 v80, v80
	v_exp_f32_e32 v81, v81
	v_exp_f32_e32 v82, v82
	v_exp_f32_e32 v83, v83
	v_mov_b32_e32 v176, v80
	v_mov_b32_e32 v177, v81
	v_cvt_pk_bf16_f32 v80, v80, v81
	v_add_f32_e32 v176, v82, v176
	s_waitcnt lgkmcnt(8)
	v_mfma_f32_32x32x16_bf16 v[48:63], v[196:199], v[110:113], v[224:239]
	ds_read_b128 v[196:199], v126 offset:6144
	ds_read_b64_tr_b16 v[240:241], v139 offset:21504
	ds_read_b64_tr_b16 v[242:243], v139 offset:22016
	v_add_f32_e32 v177, v83, v177
	v_cvt_pk_bf16_f32 v81, v82, v83
	v_exp_f32_e32 v84, v84
	v_exp_f32_e32 v85, v85
	v_mfma_f32_32x32x16_bf16 v[32:47], v[200:203], v[110:113], v[224:239]
	ds_read_b128 v[200:203], v126 offset:6656
	ds_read_b64_tr_b16 v[122:123], v139 offset:25600
	ds_read_b64_tr_b16 v[124:125], v139 offset:26112
	v_exp_f32_e32 v86, v86
	v_exp_f32_e32 v87, v87
	v_add_f32_e32 v176, v84, v176
	v_add_f32_e32 v177, v85, v177
	s_waitcnt lgkmcnt(12)
	v_mfma_f32_32x32x16_bf16 v[48:63], v[204:207], v[106:109], v[48:63]
	ds_read_b128 v[204:207], v126 offset:8192
	v_cvt_pk_bf16_f32 v82, v84, v85
	v_add_f32_e32 v176, v86, v176
	v_add_f32_e32 v177, v87, v177
	v_cvt_pk_bf16_f32 v83, v86, v87
	v_mfma_f32_32x32x16_bf16 v[32:47], v[208:211], v[106:109], v[32:47]
	ds_read_b128 v[208:211], v126 offset:8704
	v_exp_f32_e32 v88, v88
	v_exp_f32_e32 v89, v89
	v_exp_f32_e32 v90, v90
	v_exp_f32_e32 v91, v91
	s_waitcnt lgkmcnt(8)
	v_mfma_f32_32x32x16_bf16 v[48:63], v[212:215], v[114:117], v[48:63]
	ds_read_b128 v[212:215], v126 offset:10240
	v_add_f32_e32 v176, v88, v176
	v_add_f32_e32 v177, v89, v177
	v_cvt_pk_bf16_f32 v84, v88, v89
	v_add_f32_e32 v176, v90, v176
	v_mfma_f32_32x32x16_bf16 v[0:15], v[80:83], v[220:223], v[0:15]
	ds_read_b64_tr_b16 v[220:221], v139 offset:22528
	ds_read_b64_tr_b16 v[222:223], v139 offset:23040
	v_add_f32_e32 v177, v91, v177
	v_cvt_pk_bf16_f32 v85, v90, v91
	v_exp_f32_e32 v92, v92
	v_exp_f32_e32 v93, v93
	v_mfma_f32_32x32x16_bf16 v[16:31], v[80:83], v[244:247], v[16:31]
	ds_read_b64_tr_b16 v[244:245], v139 offset:26624
	ds_read_b64_tr_b16 v[246:247], v139 offset:27136
	v_exp_f32_e32 v94, v94
	v_exp_f32_e32 v95, v95
	v_add_f32_e32 v176, v92, v176
	v_add_f32_e32 v177, v93, v177
	v_mfma_f32_32x32x16_bf16 v[32:47], v[216:219], v[114:117], v[32:47]
	ds_read_b128 v[216:219], v126 offset:10752
	v_cvt_pk_bf16_f32 v86, v92, v93
	v_add_f32_e32 v176, v94, v176
	v_add_f32_e32 v177, v95, v177
	v_cvt_pk_bf16_f32 v87, v94, v95
	s_waitcnt lgkmcnt(10)
	v_mfma_f32_32x32x16_bf16 v[48:63], v[196:199], v[118:121], v[48:63]
	v_exp_f32_e32 v64, v64
	v_exp_f32_e32 v65, v65
	v_exp_f32_e32 v66, v66
	v_exp_f32_e32 v67, v67
	v_mfma_f32_32x32x16_bf16 v[32:47], v[200:203], v[118:121], v[32:47]
	v_add_f32_e32 v176, v64, v176
	v_add_f32_e32 v177, v65, v177
	v_cvt_pk_bf16_f32 v64, v64, v65
	v_add_f32_e32 v176, v66, v176
	s_waitcnt lgkmcnt(8)
	v_mfma_f32_32x32x16_bf16 v[0:15], v[84:87], v[240:243], v[0:15]
	ds_read_b64_tr_b16 v[240:241], v139 offset:23552
	ds_read_b64_tr_b16 v[242:243], v139 offset:24064
	v_add_f32_e32 v177, v67, v177
	v_cvt_pk_bf16_f32 v65, v66, v67
	v_exp_f32_e32 v68, v68
	v_exp_f32_e32 v69, v69
	v_mfma_f32_32x32x16_bf16 v[16:31], v[84:87], v[122:125], v[16:31]
	ds_read_b64_tr_b16 v[122:123], v139 offset:27648
	ds_read_b64_tr_b16 v[124:125], v139 offset:28160
	v_exp_f32_e32 v70, v70
	v_exp_f32_e32 v71, v71
	v_add_f32_e32 v176, v68, v176
	v_add_f32_e32 v177, v69, v177
	s_waitcnt lgkmcnt(10)
	v_mfma_f32_32x32x16_bf16 v[48:63], v[204:207], v[102:105], v[48:63]
	v_cvt_pk_bf16_f32 v66, v68, v69
	v_add_f32_e32 v176, v70, v176
	v_add_f32_e32 v177, v71, v177
	v_cvt_pk_bf16_f32 v67, v70, v71
	v_mfma_f32_32x32x16_bf16 v[32:47], v[208:211], v[102:105], v[32:47]
	v_exp_f32_e32 v72, v72
	v_exp_f32_e32 v73, v73
	v_exp_f32_e32 v74, v74
	v_exp_f32_e32 v75, v75
	s_waitcnt vmcnt(1)
	s_barrier
	s_waitcnt lgkmcnt(5)
	v_mfma_f32_32x32x16_bf16 v[0:15], v[64:67], v[220:223], v[0:15]
	ds_read_b128 v[196:199], v126 offset:20480
	ds_read_b128 v[200:203], v126 offset:20992
	ds_read_b128 v[204:207], v126 offset:22528
	ds_read_b128 v[208:211], v126 offset:23040
	ds_read_b64_tr_b16 v[220:221], v127 offset:0
	ds_read_b64_tr_b16 v[222:223], v127 offset:512
	v_add_f32_e32 v176, v72, v176
	v_add_f32_e32 v177, v73, v177
	v_cvt_pk_bf16_f32 v68, v72, v73
	v_add_f32_e32 v176, v74, v176
	v_mfma_f32_32x32x16_bf16 v[16:31], v[64:67], v[244:247], v[16:31]
	ds_read_b64_tr_b16 v[244:245], v127 offset:4096
	ds_read_b64_tr_b16 v[246:247], v127 offset:4608
	v_add_f32_e32 v177, v75, v177
	v_cvt_pk_bf16_f32 v69, v74, v75
	v_exp_f32_e32 v76, v76
	v_exp_f32_e32 v77, v77
	s_waitcnt lgkmcnt(12)
	v_mfma_f32_32x32x16_bf16 v[48:63], v[212:215], v[98:101], v[48:63]
	ds_read_b128 v[212:215], v126 offset:24576
	v_exp_f32_e32 v78, v78
	v_exp_f32_e32 v79, v79
	v_add_f32_e32 v176, v76, v176
	v_add_f32_e32 v177, v77, v177
	v_mfma_f32_32x32x16_bf16 v[32:47], v[216:219], v[98:101], v[32:47]
	ds_read_b128 v[216:219], v126 offset:25088
	v_cvt_pk_bf16_f32 v70, v76, v77
	v_add_f32_e32 v176, v78, v176
	v_add_f32_e32 v177, v79, v177
	v_cvt_pk_bf16_f32 v71, v78, v79
	s_waitcnt lgkmcnt(10)
	v_mfma_f32_32x32x16_bf16 v[0:15], v[68:71], v[240:243], v[0:15]
	v_add_f32_e32 v175, v176, v177
	v_mov_b32_e32 v178, v175
	v_add_f32_e32 v147, v147, v175
	s_nop 0
	v_mfma_f32_32x32x16_bf16 v[16:31], v[68:71], v[122:125], v[16:31]
	v_permlane32_swap_b32_e32 v175, v178
	v_add_f32_e32 v175, v175, v178
	v_cmp_lt_f32_e32 vcc, 0x43800000, v175
	s_cbranch_vccz .Lat_nr_23
	v_log_f32_e32 v175, v175
	s_nop 0
	v_max_f32_e32 v175, 0, v175
	v_exp_f32_e64 v178, -v175
	s_and_saveexec_b64 s[4:5], s[2:3]
	ds_write_b32 v143, v178 offset:40960
	s_or_b64 exec, exec, s[4:5]
	s_waitcnt lgkmcnt(0)
	v_add_u32_e32 v179, s33, v191
	v_sub_f32_e32 v224, v224, v175
	v_mul_f32_e32 v147, v147, v178
	ds_read_b128 v[80:83], v179 offset:40960
	ds_read_b128 v[84:87], v179 offset:40992
	ds_read_b128 v[88:91], v179 offset:41024
	ds_read_b128 v[92:95], v179 offset:41056
	s_waitcnt lgkmcnt(0)
	s_nop 15
	v_pk_mul_f32 v[0:1], v[0:1], v[80:81]
	v_pk_mul_f32 v[2:3], v[2:3], v[82:83]
	v_pk_mul_f32 v[4:5], v[4:5], v[84:85]
	v_pk_mul_f32 v[6:7], v[6:7], v[86:87]
	v_pk_mul_f32 v[8:9], v[8:9], v[88:89]
	v_pk_mul_f32 v[10:11], v[10:11], v[90:91]
	v_pk_mul_f32 v[12:13], v[12:13], v[92:93]
	v_pk_mul_f32 v[14:15], v[14:15], v[94:95]
	v_pk_mul_f32 v[16:17], v[16:17], v[80:81]
	v_pk_mul_f32 v[18:19], v[18:19], v[82:83]
	v_pk_mul_f32 v[20:21], v[20:21], v[84:85]
	v_pk_mul_f32 v[22:23], v[22:23], v[86:87]
	v_pk_mul_f32 v[24:25], v[24:25], v[88:89]
	v_pk_mul_f32 v[26:27], v[26:27], v[90:91]
	v_pk_mul_f32 v[28:29], v[28:29], v[92:93]
	v_pk_mul_f32 v[30:31], v[30:31], v[94:95]
	v_mov_b32_e32 v225, v224
	v_mov_b32_e32 v226, v224
	v_mov_b32_e32 v227, v224
	v_mov_b32_e32 v228, v224
	v_mov_b32_e32 v229, v224
	v_mov_b32_e32 v230, v224
	v_mov_b32_e32 v231, v224
	v_mov_b32_e32 v232, v224
	v_mov_b32_e32 v233, v224
	v_mov_b32_e32 v234, v224
	v_mov_b32_e32 v235, v224
	v_mov_b32_e32 v236, v224
	v_mov_b32_e32 v237, v224
	v_mov_b32_e32 v238, v224
	v_mov_b32_e32 v239, v224
	v_sub_f32_e32 v48, v48, v175
	v_sub_f32_e32 v49, v49, v175
	v_sub_f32_e32 v50, v50, v175
	v_sub_f32_e32 v51, v51, v175
	v_sub_f32_e32 v52, v52, v175
	v_sub_f32_e32 v53, v53, v175
	v_sub_f32_e32 v54, v54, v175
	v_sub_f32_e32 v55, v55, v175
	v_sub_f32_e32 v56, v56, v175
	v_sub_f32_e32 v57, v57, v175
	v_sub_f32_e32 v58, v58, v175
	v_sub_f32_e32 v59, v59, v175
	v_sub_f32_e32 v60, v60, v175
	v_sub_f32_e32 v61, v61, v175
	v_sub_f32_e32 v62, v62, v175
	v_sub_f32_e32 v63, v63, v175
	v_sub_f32_e32 v32, v32, v175
	v_sub_f32_e32 v33, v33, v175
	v_sub_f32_e32 v34, v34, v175
	v_sub_f32_e32 v35, v35, v175
	v_sub_f32_e32 v36, v36, v175
	v_sub_f32_e32 v37, v37, v175
	v_sub_f32_e32 v38, v38, v175
	v_sub_f32_e32 v39, v39, v175
	v_sub_f32_e32 v40, v40, v175
	v_sub_f32_e32 v41, v41, v175
	v_sub_f32_e32 v42, v42, v175
	v_sub_f32_e32 v43, v43, v175
	v_sub_f32_e32 v44, v44, v175
	v_sub_f32_e32 v45, v45, v175
	v_sub_f32_e32 v46, v46, v175
	v_sub_f32_e32 v47, v47, v175
.Lat_nr_23:
	v_exp_f32_e32 v48, v48
	v_exp_f32_e32 v49, v49
	v_exp_f32_e32 v50, v50
	v_exp_f32_e32 v51, v51
	v_mov_b32_e32 v176, v48
	v_mov_b32_e32 v177, v49
	v_cvt_pk_bf16_f32 v48, v48, v49
	v_add_f32_e32 v176, v50, v176
	s_waitcnt lgkmcnt(8)
	v_mfma_f32_32x32x16_bf16 v[80:95], v[196:199], v[110:113], v[224:239]
	ds_read_b128 v[196:199], v126 offset:26624
	ds_read_b64_tr_b16 v[240:241], v127 offset:1024
	ds_read_b64_tr_b16 v[242:243], v127 offset:1536
	v_add_f32_e32 v177, v51, v177
	v_cvt_pk_bf16_f32 v49, v50, v51
	v_exp_f32_e32 v52, v52
	v_exp_f32_e32 v53, v53
	v_mfma_f32_32x32x16_bf16 v[64:79], v[200:203], v[110:113], v[224:239]
	ds_read_b128 v[200:203], v126 offset:27136
	ds_read_b64_tr_b16 v[122:123], v127 offset:5120
	ds_read_b64_tr_b16 v[124:125], v127 offset:5632
	v_exp_f32_e32 v54, v54
	v_exp_f32_e32 v55, v55
	v_add_f32_e32 v176, v52, v176
	v_add_f32_e32 v177, v53, v177
	s_waitcnt lgkmcnt(12)
	v_mfma_f32_32x32x16_bf16 v[80:95], v[204:207], v[106:109], v[80:95]
	ds_read_b128 v[204:207], v126 offset:28672
	v_cvt_pk_bf16_f32 v50, v52, v53
	v_add_f32_e32 v176, v54, v176
	v_add_f32_e32 v177, v55, v177
	v_cvt_pk_bf16_f32 v51, v54, v55
	v_mfma_f32_32x32x16_bf16 v[64:79], v[208:211], v[106:109], v[64:79]
	ds_read_b128 v[208:211], v126 offset:29184
	v_exp_f32_e32 v56, v56
	v_exp_f32_e32 v57, v57
	v_exp_f32_e32 v58, v58
	v_exp_f32_e32 v59, v59
	s_waitcnt lgkmcnt(8)
	v_mfma_f32_32x32x16_bf16 v[80:95], v[212:215], v[114:117], v[80:95]
	ds_read_b128 v[212:215], v126 offset:30720
	v_add_f32_e32 v176, v56, v176
	v_add_f32_e32 v177, v57, v177
	v_cvt_pk_bf16_f32 v52, v56, v57
	v_add_f32_e32 v176, v58, v176
	v_mfma_f32_32x32x16_bf16 v[0:15], v[48:51], v[220:223], v[0:15]
	ds_read_b64_tr_b16 v[220:221], v127 offset:2048
	ds_read_b64_tr_b16 v[222:223], v127 offset:2560
	v_add_f32_e32 v177, v59, v177
	v_cvt_pk_bf16_f32 v53, v58, v59
	v_exp_f32_e32 v60, v60
	v_exp_f32_e32 v61, v61
	v_mfma_f32_32x32x16_bf16 v[16:31], v[48:51], v[244:247], v[16:31]
	ds_read_b64_tr_b16 v[244:245], v127 offset:6144
	ds_read_b64_tr_b16 v[246:247], v127 offset:6656
	v_exp_f32_e32 v62, v62
	v_exp_f32_e32 v63, v63
	v_add_f32_e32 v176, v60, v176
	v_add_f32_e32 v177, v61, v177
	v_mfma_f32_32x32x16_bf16 v[64:79], v[216:219], v[114:117], v[64:79]
	ds_read_b128 v[216:219], v126 offset:31232
	v_cvt_pk_bf16_f32 v54, v60, v61
	v_add_f32_e32 v176, v62, v176
	v_add_f32_e32 v177, v63, v177
	v_cvt_pk_bf16_f32 v55, v62, v63
	s_waitcnt lgkmcnt(10)
	v_mfma_f32_32x32x16_bf16 v[80:95], v[196:199], v[118:121], v[80:95]
	v_exp_f32_e32 v32, v32
	v_exp_f32_e32 v33, v33
	v_exp_f32_e32 v34, v34
	v_exp_f32_e32 v35, v35
	v_mfma_f32_32x32x16_bf16 v[64:79], v[200:203], v[118:121], v[64:79]
	v_add_f32_e32 v176, v32, v176
	v_add_f32_e32 v177, v33, v177
	v_cvt_pk_bf16_f32 v32, v32, v33
	v_add_f32_e32 v176, v34, v176
	s_waitcnt lgkmcnt(8)
	v_mfma_f32_32x32x16_bf16 v[0:15], v[52:55], v[240:243], v[0:15]
	ds_read_b64_tr_b16 v[240:241], v127 offset:3072
	ds_read_b64_tr_b16 v[242:243], v127 offset:3584
	v_add_f32_e32 v177, v35, v177
	v_cvt_pk_bf16_f32 v33, v34, v35
	v_exp_f32_e32 v36, v36
	v_exp_f32_e32 v37, v37
	v_mfma_f32_32x32x16_bf16 v[16:31], v[52:55], v[122:125], v[16:31]
	ds_read_b64_tr_b16 v[122:123], v127 offset:7168
	ds_read_b64_tr_b16 v[124:125], v127 offset:7680
	v_exp_f32_e32 v38, v38
	v_exp_f32_e32 v39, v39
	v_add_f32_e32 v176, v36, v176
	v_add_f32_e32 v177, v37, v177
	s_waitcnt lgkmcnt(10)
	v_mfma_f32_32x32x16_bf16 v[80:95], v[204:207], v[102:105], v[80:95]
	v_cvt_pk_bf16_f32 v34, v36, v37
	v_add_f32_e32 v176, v38, v176
	v_add_f32_e32 v177, v39, v177
	v_cvt_pk_bf16_f32 v35, v38, v39
	v_mfma_f32_32x32x16_bf16 v[64:79], v[208:211], v[102:105], v[64:79]
	v_exp_f32_e32 v40, v40
	v_exp_f32_e32 v41, v41
	v_exp_f32_e32 v42, v42
	v_exp_f32_e32 v43, v43
	s_waitcnt vmcnt(0)
	s_barrier
	s_waitcnt lgkmcnt(5)
	v_mfma_f32_32x32x16_bf16 v[0:15], v[32:35], v[220:223], v[0:15]
	ds_read_b64_tr_b16 v[220:221], v127 offset:20480
	ds_read_b64_tr_b16 v[222:223], v127 offset:20992
	v_add_f32_e32 v176, v40, v176
	v_add_f32_e32 v177, v41, v177
	v_cvt_pk_bf16_f32 v36, v40, v41
	v_add_f32_e32 v176, v42, v176
	v_mfma_f32_32x32x16_bf16 v[16:31], v[32:35], v[244:247], v[16:31]
	ds_read_b64_tr_b16 v[244:245], v127 offset:24576
	ds_read_b64_tr_b16 v[246:247], v127 offset:25088
	v_add_f32_e32 v177, v43, v177
	v_cvt_pk_bf16_f32 v37, v42, v43
	v_exp_f32_e32 v44, v44
	v_exp_f32_e32 v45, v45
	s_waitcnt lgkmcnt(8)
	v_mfma_f32_32x32x16_bf16 v[80:95], v[212:215], v[98:101], v[80:95]
	v_exp_f32_e32 v46, v46
	v_exp_f32_e32 v47, v47
	v_add_f32_e32 v176, v44, v176
	v_add_f32_e32 v177, v45, v177
	v_mfma_f32_32x32x16_bf16 v[64:79], v[216:219], v[98:101], v[64:79]
	v_cvt_pk_bf16_f32 v38, v44, v45
	v_add_f32_e32 v176, v46, v176
	v_add_f32_e32 v177, v47, v177
	v_cvt_pk_bf16_f32 v39, v46, v47
	s_waitcnt lgkmcnt(4)
	v_mfma_f32_32x32x16_bf16 v[0:15], v[36:39], v[240:243], v[0:15]
	v_add_f32_e32 v175, v176, v177
	v_mov_b32_e32 v178, v175
	v_add_f32_e32 v147, v147, v175
	s_nop 0
	v_mfma_f32_32x32x16_bf16 v[16:31], v[36:39], v[122:125], v[16:31]
	v_permlane32_swap_b32_e32 v175, v178
	v_add_f32_e32 v175, v175, v178
	v_cmp_lt_f32_e32 vcc, 0x43800000, v175
	s_cbranch_vccz .Lat_nr_24
	v_log_f32_e32 v175, v175
	s_nop 0
	v_max_f32_e32 v175, 0, v175
	v_exp_f32_e64 v178, -v175
	s_and_saveexec_b64 s[4:5], s[2:3]
	ds_write_b32 v143, v178 offset:40960
	s_or_b64 exec, exec, s[4:5]
	s_waitcnt lgkmcnt(0)
	v_add_u32_e32 v179, s33, v191
	v_sub_f32_e32 v224, v224, v175
	v_mul_f32_e32 v147, v147, v178
	ds_read_b128 v[48:51], v179 offset:40960
	ds_read_b128 v[52:55], v179 offset:40992
	ds_read_b128 v[56:59], v179 offset:41024
	ds_read_b128 v[60:63], v179 offset:41056
	s_waitcnt lgkmcnt(0)
	s_nop 15
	v_pk_mul_f32 v[0:1], v[0:1], v[48:49]
	v_pk_mul_f32 v[2:3], v[2:3], v[50:51]
	v_pk_mul_f32 v[4:5], v[4:5], v[52:53]
	v_pk_mul_f32 v[6:7], v[6:7], v[54:55]
	v_pk_mul_f32 v[8:9], v[8:9], v[56:57]
	v_pk_mul_f32 v[10:11], v[10:11], v[58:59]
	v_pk_mul_f32 v[12:13], v[12:13], v[60:61]
	v_pk_mul_f32 v[14:15], v[14:15], v[62:63]
	v_pk_mul_f32 v[16:17], v[16:17], v[48:49]
	v_pk_mul_f32 v[18:19], v[18:19], v[50:51]
	v_pk_mul_f32 v[20:21], v[20:21], v[52:53]
	v_pk_mul_f32 v[22:23], v[22:23], v[54:55]
	v_pk_mul_f32 v[24:25], v[24:25], v[56:57]
	v_pk_mul_f32 v[26:27], v[26:27], v[58:59]
	v_pk_mul_f32 v[28:29], v[28:29], v[60:61]
	v_pk_mul_f32 v[30:31], v[30:31], v[62:63]
	v_mov_b32_e32 v225, v224
	v_mov_b32_e32 v226, v224
	v_mov_b32_e32 v227, v224
	v_mov_b32_e32 v228, v224
	v_mov_b32_e32 v229, v224
	v_mov_b32_e32 v230, v224
	v_mov_b32_e32 v231, v224
	v_mov_b32_e32 v232, v224
	v_mov_b32_e32 v233, v224
	v_mov_b32_e32 v234, v224
	v_mov_b32_e32 v235, v224
	v_mov_b32_e32 v236, v224
	v_mov_b32_e32 v237, v224
	v_mov_b32_e32 v238, v224
	v_mov_b32_e32 v239, v224
	v_sub_f32_e32 v80, v80, v175
	v_sub_f32_e32 v81, v81, v175
	v_sub_f32_e32 v82, v82, v175
	v_sub_f32_e32 v83, v83, v175
	v_sub_f32_e32 v84, v84, v175
	v_sub_f32_e32 v85, v85, v175
	v_sub_f32_e32 v86, v86, v175
	v_sub_f32_e32 v87, v87, v175
	v_sub_f32_e32 v88, v88, v175
	v_sub_f32_e32 v89, v89, v175
	v_sub_f32_e32 v90, v90, v175
	v_sub_f32_e32 v91, v91, v175
	v_sub_f32_e32 v92, v92, v175
	v_sub_f32_e32 v93, v93, v175
	v_sub_f32_e32 v94, v94, v175
	v_sub_f32_e32 v95, v95, v175
	v_sub_f32_e32 v64, v64, v175
	v_sub_f32_e32 v65, v65, v175
	v_sub_f32_e32 v66, v66, v175
	v_sub_f32_e32 v67, v67, v175
	v_sub_f32_e32 v68, v68, v175
	v_sub_f32_e32 v69, v69, v175
	v_sub_f32_e32 v70, v70, v175
	v_sub_f32_e32 v71, v71, v175
	v_sub_f32_e32 v72, v72, v175
	v_sub_f32_e32 v73, v73, v175
	v_sub_f32_e32 v74, v74, v175
	v_sub_f32_e32 v75, v75, v175
	v_sub_f32_e32 v76, v76, v175
	v_sub_f32_e32 v77, v77, v175
	v_sub_f32_e32 v78, v78, v175
	v_sub_f32_e32 v79, v79, v175
.Lat_nr_24:
	v_exp_f32_e32 v80, v80
	v_exp_f32_e32 v81, v81
	v_exp_f32_e32 v82, v82
	v_exp_f32_e32 v83, v83
	v_mov_b32_e32 v176, v80
	v_mov_b32_e32 v177, v81
	v_cvt_pk_bf16_f32 v80, v80, v81
	v_add_f32_e32 v176, v82, v176
	ds_read_b64_tr_b16 v[240:241], v127 offset:21504
	ds_read_b64_tr_b16 v[242:243], v127 offset:22016
	v_add_f32_e32 v177, v83, v177
	v_cvt_pk_bf16_f32 v81, v82, v83
	v_exp_f32_e32 v84, v84
	v_exp_f32_e32 v85, v85
	ds_read_b64_tr_b16 v[122:123], v127 offset:25600
	ds_read_b64_tr_b16 v[124:125], v127 offset:26112
	v_exp_f32_e32 v86, v86
	v_exp_f32_e32 v87, v87
	v_add_f32_e32 v176, v84, v176
	v_add_f32_e32 v177, v85, v177
	v_cvt_pk_bf16_f32 v82, v84, v85
	v_add_f32_e32 v176, v86, v176
	v_add_f32_e32 v177, v87, v177
	v_cvt_pk_bf16_f32 v83, v86, v87
	v_exp_f32_e32 v88, v88
	v_exp_f32_e32 v89, v89
	v_exp_f32_e32 v90, v90
	v_exp_f32_e32 v91, v91
	v_add_f32_e32 v176, v88, v176
	v_add_f32_e32 v177, v89, v177
	v_cvt_pk_bf16_f32 v84, v88, v89
	v_add_f32_e32 v176, v90, v176
	s_waitcnt lgkmcnt(4)
	v_mfma_f32_32x32x16_bf16 v[0:15], v[80:83], v[220:223], v[0:15]
	ds_read_b64_tr_b16 v[220:221], v127 offset:22528
	ds_read_b64_tr_b16 v[222:223], v127 offset:23040
	v_add_f32_e32 v177, v91, v177
	v_cvt_pk_bf16_f32 v85, v90, v91
	v_exp_f32_e32 v92, v92
	v_exp_f32_e32 v93, v93
	v_mfma_f32_32x32x16_bf16 v[16:31], v[80:83], v[244:247], v[16:31]
	ds_read_b64_tr_b16 v[244:245], v127 offset:26624
	ds_read_b64_tr_b16 v[246:247], v127 offset:27136
	v_exp_f32_e32 v94, v94
	v_exp_f32_e32 v95, v95
	v_add_f32_e32 v176, v92, v176
	v_add_f32_e32 v177, v93, v177
	v_cvt_pk_bf16_f32 v86, v92, v93
	v_add_f32_e32 v176, v94, v176
	v_add_f32_e32 v177, v95, v177
	v_cvt_pk_bf16_f32 v87, v94, v95
	v_exp_f32_e32 v64, v64
	v_exp_f32_e32 v65, v65
	v_exp_f32_e32 v66, v66
	v_exp_f32_e32 v67, v67
	v_add_f32_e32 v176, v64, v176
	v_add_f32_e32 v177, v65, v177
	v_cvt_pk_bf16_f32 v64, v64, v65
	v_add_f32_e32 v176, v66, v176
	s_waitcnt lgkmcnt(4)
	v_mfma_f32_32x32x16_bf16 v[0:15], v[84:87], v[240:243], v[0:15]
	ds_read_b64_tr_b16 v[240:241], v127 offset:23552
	ds_read_b64_tr_b16 v[242:243], v127 offset:24064
	v_add_f32_e32 v177, v67, v177
	v_cvt_pk_bf16_f32 v65, v66, v67
	v_exp_f32_e32 v68, v68
	v_exp_f32_e32 v69, v69
	v_mfma_f32_32x32x16_bf16 v[16:31], v[84:87], v[122:125], v[16:31]
	ds_read_b64_tr_b16 v[122:123], v127 offset:27648
	ds_read_b64_tr_b16 v[124:125], v127 offset:28160
	v_exp_f32_e32 v70, v70
	v_exp_f32_e32 v71, v71
	v_add_f32_e32 v176, v68, v176
	v_add_f32_e32 v177, v69, v177
	v_cvt_pk_bf16_f32 v66, v68, v69
	v_add_f32_e32 v176, v70, v176
	v_add_f32_e32 v177, v71, v177
	v_cvt_pk_bf16_f32 v67, v70, v71
	v_exp_f32_e32 v72, v72
	v_exp_f32_e32 v73, v73
	v_exp_f32_e32 v74, v74
	v_exp_f32_e32 v75, v75
	s_waitcnt vmcnt(0)
	s_barrier
	s_waitcnt lgkmcnt(4)
	v_mfma_f32_32x32x16_bf16 v[0:15], v[64:67], v[220:223], v[0:15]
	v_add_f32_e32 v176, v72, v176
	v_add_f32_e32 v177, v73, v177
	v_cvt_pk_bf16_f32 v68, v72, v73
	v_add_f32_e32 v176, v74, v176
	v_mfma_f32_32x32x16_bf16 v[16:31], v[64:67], v[244:247], v[16:31]
	v_add_f32_e32 v177, v75, v177
	v_cvt_pk_bf16_f32 v69, v74, v75
	v_exp_f32_e32 v76, v76
	v_exp_f32_e32 v77, v77
	v_exp_f32_e32 v78, v78
	v_exp_f32_e32 v79, v79
	v_add_f32_e32 v176, v76, v176
	v_add_f32_e32 v177, v77, v177
	v_cvt_pk_bf16_f32 v70, v76, v77
	v_add_f32_e32 v176, v78, v176
	v_add_f32_e32 v177, v79, v177
	v_cvt_pk_bf16_f32 v71, v78, v79
	s_waitcnt lgkmcnt(0)
	v_mfma_f32_32x32x16_bf16 v[0:15], v[68:71], v[240:243], v[0:15]
	v_add_f32_e32 v175, v176, v177
	v_mov_b32_e32 v178, v175
	v_add_f32_e32 v147, v147, v175
	s_nop 0
	v_mfma_f32_32x32x16_bf16 v[16:31], v[68:71], v[122:125], v[16:31]
	v_permlane32_swap_b32_e32 v175, v178
	v_add_f32_e32 v175, v175, v178
	v_cmp_lt_f32_e32 vcc, 0x43800000, v175
	s_cbranch_vccz .Lat_nr_25
	v_log_f32_e32 v175, v175
	s_nop 0
	v_max_f32_e32 v175, 0, v175
	v_exp_f32_e64 v178, -v175
	s_and_saveexec_b64 s[4:5], s[2:3]
	ds_write_b32 v143, v178 offset:40960
	s_or_b64 exec, exec, s[4:5]
	s_waitcnt lgkmcnt(0)
	v_add_u32_e32 v179, s33, v191
	v_sub_f32_e32 v224, v224, v175
	v_mul_f32_e32 v147, v147, v178
	ds_read_b128 v[80:83], v179 offset:40960
	ds_read_b128 v[84:87], v179 offset:40992
	ds_read_b128 v[88:91], v179 offset:41024
	ds_read_b128 v[92:95], v179 offset:41056
	s_waitcnt lgkmcnt(0)
	s_nop 15
	v_pk_mul_f32 v[0:1], v[0:1], v[80:81]
	v_pk_mul_f32 v[2:3], v[2:3], v[82:83]
	v_pk_mul_f32 v[4:5], v[4:5], v[84:85]
	v_pk_mul_f32 v[6:7], v[6:7], v[86:87]
	v_pk_mul_f32 v[8:9], v[8:9], v[88:89]
	v_pk_mul_f32 v[10:11], v[10:11], v[90:91]
	v_pk_mul_f32 v[12:13], v[12:13], v[92:93]
	v_pk_mul_f32 v[14:15], v[14:15], v[94:95]
	v_pk_mul_f32 v[16:17], v[16:17], v[80:81]
	v_pk_mul_f32 v[18:19], v[18:19], v[82:83]
	v_pk_mul_f32 v[20:21], v[20:21], v[84:85]
	v_pk_mul_f32 v[22:23], v[22:23], v[86:87]
	v_pk_mul_f32 v[24:25], v[24:25], v[88:89]
	v_pk_mul_f32 v[26:27], v[26:27], v[90:91]
	v_pk_mul_f32 v[28:29], v[28:29], v[92:93]
	v_pk_mul_f32 v[30:31], v[30:31], v[94:95]
	v_mov_b32_e32 v225, v224
	v_mov_b32_e32 v226, v224
	v_mov_b32_e32 v227, v224
	v_mov_b32_e32 v228, v224
	v_mov_b32_e32 v229, v224
	v_mov_b32_e32 v230, v224
	v_mov_b32_e32 v231, v224
	v_mov_b32_e32 v232, v224
	v_mov_b32_e32 v233, v224
	v_mov_b32_e32 v234, v224
	v_mov_b32_e32 v235, v224
	v_mov_b32_e32 v236, v224
	v_mov_b32_e32 v237, v224
	v_mov_b32_e32 v238, v224
	v_mov_b32_e32 v239, v224
